# attention QK and PV segments: LDS fragment reads issued earlier with renamed registers, lgkmcnt waits re-derived (on top of epilogue load batching and scan edits)
# baseline (speedup 1.0000x reference)
.LBB0_1136:
	s_and_b32 s55, s9, 1
	s_mul_i32 s10, s55, 0x6000
	s_add_i32 s10, s10, 0
	v_add3_u32 v2, s10, v206, v189
	ds_read_b128 v[68:71], v2 offset:32768
	ds_read_b128 v[72:75], v2 offset:45056
	v_add3_u32 v2, s10, v205, v189
	ds_read_b128 v[208:211], v2 offset:32768
	ds_read_b128 v[212:215], v2 offset:45056
	v_add3_u32 v2, s10, v204, v189
	ds_read_b128 v[216:219], v2 offset:32768
	ds_read_b128 v[220:223], v2 offset:45056
	s_waitcnt vmcnt(16)
	s_waitcnt lgkmcnt(5)
	v_mfma_f32_32x32x16_bf16 v[84:99], v[68:71], v[144:147], 0
	s_waitcnt lgkmcnt(4)
	v_mfma_f32_32x32x16_bf16 v[68:83], v[72:75], v[144:147], 0
	s_waitcnt vmcnt(15)
	s_waitcnt lgkmcnt(3)
	v_mfma_f32_32x32x16_bf16 v[84:99], v[208:211], v[140:143], v[84:99]
	s_waitcnt lgkmcnt(2)
	v_mfma_f32_32x32x16_bf16 v[68:83], v[212:215], v[140:143], v[68:83]
	v_add3_u32 v2, s10, v203, v189
	ds_read_b128 v[208:211], v2 offset:32768
	ds_read_b128 v[212:215], v2 offset:45056
	s_waitcnt vmcnt(14)
	s_waitcnt lgkmcnt(3)
	v_mfma_f32_32x32x16_bf16 v[84:99], v[216:219], v[136:139], v[84:99]
	s_waitcnt lgkmcnt(2)
	v_mfma_f32_32x32x16_bf16 v[68:83], v[220:223], v[136:139], v[68:83]
	v_add3_u32 v2, s10, v202, v189
	ds_read_b128 v[216:219], v2 offset:32768
	ds_read_b128 v[220:223], v2 offset:45056
	s_waitcnt vmcnt(13)
	s_waitcnt lgkmcnt(3)
	v_mfma_f32_32x32x16_bf16 v[84:99], v[208:211], v[132:135], v[84:99]
	s_waitcnt lgkmcnt(2)
	v_mfma_f32_32x32x16_bf16 v[68:83], v[212:215], v[132:135], v[68:83]
	v_add3_u32 v2, s10, v200, v189
	ds_read_b128 v[208:211], v2 offset:32768
	ds_read_b128 v[212:215], v2 offset:45056
	s_waitcnt vmcnt(12)
	s_waitcnt lgkmcnt(3)
	v_mfma_f32_32x32x16_bf16 v[84:99], v[216:219], v[128:131], v[84:99]
	s_waitcnt lgkmcnt(2)
	v_mfma_f32_32x32x16_bf16 v[68:83], v[220:223], v[128:131], v[68:83]
	v_add3_u32 v2, s10, v198, v189
	ds_read_b128 v[216:219], v2 offset:32768
	ds_read_b128 v[220:223], v2 offset:45056
	s_waitcnt vmcnt(11)
	s_waitcnt lgkmcnt(3)
	v_mfma_f32_32x32x16_bf16 v[84:99], v[208:211], v[124:127], v[84:99]
	s_waitcnt lgkmcnt(2)
	v_mfma_f32_32x32x16_bf16 v[68:83], v[212:215], v[124:127], v[68:83]
	v_add3_u32 v2, s10, v196, v189
	ds_read_b128 v[208:211], v2 offset:32768
	ds_read_b128 v[212:215], v2 offset:45056
	s_waitcnt vmcnt(10)
	s_waitcnt lgkmcnt(3)
	v_mfma_f32_32x32x16_bf16 v[84:99], v[216:219], v[120:123], v[84:99]
	s_waitcnt lgkmcnt(2)
	v_mfma_f32_32x32x16_bf16 v[68:83], v[220:223], v[120:123], v[68:83]
	v_add3_u32 v2, s10, v194, v189
	ds_read_b128 v[216:219], v2 offset:32768
	ds_read_b128 v[220:223], v2 offset:45056
	s_waitcnt vmcnt(9)
	s_waitcnt lgkmcnt(3)
	v_mfma_f32_32x32x16_bf16 v[84:99], v[208:211], v[116:119], v[84:99]
	s_waitcnt lgkmcnt(2)
	v_mfma_f32_32x32x16_bf16 v[68:83], v[212:215], v[116:119], v[68:83]
	v_add3_u32 v2, s10, v193, v189
	ds_read_b128 v[208:211], v2 offset:32768
	ds_read_b128 v[212:215], v2 offset:45056
	s_waitcnt vmcnt(8)
	s_waitcnt lgkmcnt(3)
	v_mfma_f32_32x32x16_bf16 v[84:99], v[216:219], v[112:115], v[84:99]
	s_waitcnt lgkmcnt(2)
	v_mfma_f32_32x32x16_bf16 v[68:83], v[220:223], v[112:115], v[68:83]
	v_add3_u32 v2, s10, v192, v189
	ds_read_b128 v[216:219], v2 offset:32768
	ds_read_b128 v[220:223], v2 offset:45056
	s_waitcnt vmcnt(7)
	s_waitcnt lgkmcnt(3)
	v_mfma_f32_32x32x16_bf16 v[84:99], v[208:211], v[108:111], v[84:99]
	s_waitcnt lgkmcnt(2)
	v_mfma_f32_32x32x16_bf16 v[68:83], v[212:215], v[108:111], v[68:83]
	v_add3_u32 v2, s10, v191, v189
	ds_read_b128 v[208:211], v2 offset:32768
	ds_read_b128 v[212:215], v2 offset:45056
	s_waitcnt vmcnt(6)
	s_waitcnt lgkmcnt(3)
	v_mfma_f32_32x32x16_bf16 v[84:99], v[216:219], v[104:107], v[84:99]
	s_waitcnt vmcnt(5)
	s_waitcnt lgkmcnt(1)
	v_mfma_f32_32x32x16_bf16 v[84:99], v[208:211], v[100:103], v[84:99]
	v_max_f32_e32 v209, v190, v190
	v_mfma_f32_32x32x16_bf16 v[68:83], v[220:223], v[104:107], v[68:83]
	s_nop 9
	v_max_f32_e32 v2, v85, v85
	v_max_f32_e32 v208, v84, v84
	v_max_f32_e32 v2, v208, v2
	v_max3_f32 v2, v2, v86, v87
	v_max3_f32 v2, v2, v88, v89
	v_max3_f32 v2, v2, v90, v91
	v_max3_f32 v2, v2, v92, v93
	s_waitcnt lgkmcnt(0)
	v_mfma_f32_32x32x16_bf16 v[68:83], v[212:215], v[100:103], v[68:83]
	v_max3_f32 v2, v2, v94, v95
	v_max3_f32 v2, v2, v96, v97
	v_max3_f32 v2, v2, v98, v99
	s_nop 8
	v_max3_f32 v2, v2, v68, v69
	v_max3_f32 v2, v2, v70, v71
	v_max3_f32 v2, v2, v72, v73
	v_max3_f32 v2, v2, v74, v75
	v_max3_f32 v2, v2, v76, v77
	v_max3_f32 v2, v2, v78, v79
	v_max3_f32 v2, v2, v80, v81
	v_max3_f32 v2, v2, v82, v83
	v_mov_b32_e32 v208, v2
	s_nop 1
	v_permlane32_swap_b32_e32 v2, v208
	v_max_f32_e32 v208, v208, v208
	v_max_f32_e32 v2, v2, v2
	v_max_f32_e32 v2, v2, v208
	v_sub_f32_e32 v208, v2, v190
	v_cmp_ge_f32_e32 vcc, s38, v208
	s_cmp_eq_u64 vcc, exec
	v_max_f32_e32 v2, v209, v2
	s_cselect_b64 vcc, -1, 0
	v_sub_f32_e32 v209, v190, v2
	v_cndmask_b32_e32 v190, v2, v190, vcc
	v_mul_f32_e32 v2, 0xbdd53b94, v190
	v_fmamk_f32 v84, v84, 0x3dd53b94, v2
	v_fmamk_f32 v85, v85, 0x3dd53b94, v2
	v_fmamk_f32 v86, v86, 0x3dd53b94, v2
	v_fmamk_f32 v87, v87, 0x3dd53b94, v2
	v_fmamk_f32 v88, v88, 0x3dd53b94, v2
	v_fmamk_f32 v89, v89, 0x3dd53b94, v2
	v_fmamk_f32 v90, v90, 0x3dd53b94, v2
	v_fmamk_f32 v91, v91, 0x3dd53b94, v2
	v_fmamk_f32 v92, v92, 0x3dd53b94, v2
	v_fmamk_f32 v93, v93, 0x3dd53b94, v2
	v_fmamk_f32 v94, v94, 0x3dd53b94, v2
	v_fmamk_f32 v95, v95, 0x3dd53b94, v2
	v_fmamk_f32 v96, v96, 0x3dd53b94, v2
	v_fmamk_f32 v97, v97, 0x3dd53b94, v2
	v_fmamk_f32 v98, v98, 0x3dd53b94, v2
	v_fmamk_f32 v99, v99, 0x3dd53b94, v2
	v_fmamk_f32 v68, v68, 0x3dd53b94, v2
	v_fmamk_f32 v69, v69, 0x3dd53b94, v2
	v_fmamk_f32 v70, v70, 0x3dd53b94, v2
	v_fmamk_f32 v71, v71, 0x3dd53b94, v2
	v_fmamk_f32 v72, v72, 0x3dd53b94, v2
	v_fmamk_f32 v73, v73, 0x3dd53b94, v2
	v_fmamk_f32 v74, v74, 0x3dd53b94, v2
	v_fmamk_f32 v75, v75, 0x3dd53b94, v2
	v_fmamk_f32 v76, v76, 0x3dd53b94, v2
	v_fmamk_f32 v77, v77, 0x3dd53b94, v2
	v_fmamk_f32 v78, v78, 0x3dd53b94, v2
	v_fmamk_f32 v79, v79, 0x3dd53b94, v2
	v_fmamk_f32 v80, v80, 0x3dd53b94, v2
	v_fmamk_f32 v81, v81, 0x3dd53b94, v2
	v_fmamk_f32 v82, v82, 0x3dd53b94, v2
	v_fmac_f32_e32 v2, 0x3dd53b94, v83
	v_exp_f32_e32 v83, v84
	v_exp_f32_e32 v85, v85
	v_exp_f32_e32 v86, v86
	v_exp_f32_e32 v87, v87
	v_exp_f32_e32 v88, v88
	v_exp_f32_e32 v216, v2
	v_add_f32_e32 v2, 0, v83
	v_exp_f32_e32 v89, v89
	v_add_f32_e32 v2, v85, v2
	v_exp_f32_e32 v90, v90
	v_add_f32_e32 v2, v86, v2
	v_exp_f32_e32 v91, v91
	v_add_f32_e32 v2, v87, v2
	v_exp_f32_e32 v92, v92
	v_add_f32_e32 v2, v88, v2
	v_exp_f32_e32 v93, v93
	v_add_f32_e32 v2, v89, v2
	v_exp_f32_e32 v94, v94
	v_add_f32_e32 v2, v90, v2
	v_exp_f32_e32 v95, v95
	v_add_f32_e32 v2, v91, v2
	v_exp_f32_e32 v96, v96
	v_add_f32_e32 v2, v92, v2
	v_exp_f32_e32 v97, v97
	v_add_f32_e32 v2, v93, v2
	v_exp_f32_e32 v98, v98
	v_add_f32_e32 v2, v94, v2
	v_exp_f32_e32 v99, v99
	v_add_f32_e32 v2, v95, v2
	v_exp_f32_e32 v68, v68
	v_add_f32_e32 v2, v96, v2
	v_exp_f32_e32 v69, v69
	v_add_f32_e32 v2, v97, v2
	v_exp_f32_e32 v70, v70
	v_add_f32_e32 v2, v98, v2
	v_mul_f32_e32 v209, 0x3dd53b94, v209
	v_exp_f32_e32 v71, v71
	v_add_f32_e32 v2, v99, v2
	v_exp_f32_e32 v209, v209
	v_exp_f32_e32 v72, v72
	v_add_f32_e32 v2, v68, v2
	v_exp_f32_e32 v73, v73
	v_add_f32_e32 v2, v69, v2
	v_exp_f32_e32 v74, v74
	v_add_f32_e32 v2, v70, v2
	v_exp_f32_e32 v75, v75
	v_add_f32_e32 v2, v71, v2
	v_cndmask_b32_e64 v208, v209, 1.0, vcc
	v_exp_f32_e32 v209, v76
	v_add_f32_e32 v2, v72, v2
	v_exp_f32_e32 v210, v77
	v_add_f32_e32 v2, v73, v2
	v_exp_f32_e32 v211, v78
	v_add_f32_e32 v2, v74, v2
	v_exp_f32_e32 v212, v79
	v_add_f32_e32 v2, v75, v2
	v_exp_f32_e32 v213, v80
	v_add_f32_e32 v2, v209, v2
	v_exp_f32_e32 v214, v81
	v_add_f32_e32 v2, v210, v2
	v_exp_f32_e32 v215, v82
	v_add_f32_e32 v2, v211, v2
	v_add_f32_e32 v2, v212, v2
	v_add_f32_e32 v2, v213, v2
	v_add_f32_e32 v2, v214, v2
	v_add_f32_e32 v2, v215, v2
	v_add_f32_e32 v2, v216, v2
	v_mov_b32_e32 v84, v2
	v_cvt_pk_bf16_f32 v80, v83, v85
	v_cvt_pk_bf16_f32 v81, v86, v87
	v_cvt_pk_bf16_f32 v82, v88, v89
	v_cvt_pk_bf16_f32 v83, v90, v91
	v_cvt_pk_bf16_f32 v76, v92, v93
	v_cvt_pk_bf16_f32 v77, v94, v95
	v_cvt_pk_bf16_f32 v78, v96, v97
	v_cvt_pk_bf16_f32 v79, v98, v99
	v_cvt_pk_bf16_f32 v68, v68, v69
	v_cvt_pk_bf16_f32 v69, v70, v71
	v_cvt_pk_bf16_f32 v70, v72, v73
	v_cvt_pk_bf16_f32 v71, v74, v75
	v_cvt_pk_bf16_f32 v72, v209, v210
	v_cvt_pk_bf16_f32 v73, v211, v212
	v_cvt_pk_bf16_f32 v74, v213, v214
	v_cvt_pk_bf16_f32 v75, v215, v216
	v_permlane32_swap_b32_e32 v2, v84
	v_permlane32_swap_b32_e32 v80, v82
	v_permlane32_swap_b32_e32 v81, v83
	v_permlane32_swap_b32_e32 v76, v78
	v_permlane32_swap_b32_e32 v77, v79
	v_permlane32_swap_b32_e32 v68, v70
	v_permlane32_swap_b32_e32 v69, v71
	v_permlane32_swap_b32_e32 v72, v74
	v_permlane32_swap_b32_e32 v73, v75
	v_cmp_gt_f32_e32 vcc, 1.0, v208
	s_cbranch_vccz .LBB0_1140
	s_and_saveexec_b64 s[10:11], s[0:1]
	ds_write_b32 v182, v208 offset:128
	s_or_b64 exec, exec, s[10:11]
	s_waitcnt lgkmcnt(0)
	ds_read_b128 v[86:89], v181 offset:224
	ds_read_b128 v[90:93], v181 offset:192
	ds_read_b128 v[94:97], v181 offset:160
	ds_read_b128 v[210:213], v181 offset:128
	s_waitcnt lgkmcnt(3)
	v_pk_mul_f32 v[66:67], v[66:67], v[88:89]
	s_waitcnt lgkmcnt(2)
	v_pk_mul_f32 v[62:63], v[62:63], v[92:93]
	s_waitcnt lgkmcnt(1)
	v_pk_mul_f32 v[58:59], v[58:59], v[96:97]
	s_waitcnt lgkmcnt(0)
	v_pk_mul_f32 v[54:55], v[54:55], v[212:213]
	v_pk_mul_f32 v[64:65], v[64:65], v[86:87]
	v_pk_mul_f32 v[60:61], v[60:61], v[90:91]
	v_pk_mul_f32 v[56:57], v[56:57], v[94:95]
	v_pk_mul_f32 v[52:53], v[52:53], v[210:211]
	v_pk_mul_f32 v[50:51], v[50:51], v[88:89]
	v_pk_mul_f32 v[46:47], v[46:47], v[92:93]
	v_pk_mul_f32 v[42:43], v[42:43], v[96:97]
	v_pk_mul_f32 v[38:39], v[38:39], v[212:213]
	v_pk_mul_f32 v[48:49], v[48:49], v[86:87]
	v_pk_mul_f32 v[44:45], v[44:45], v[90:91]
	v_pk_mul_f32 v[40:41], v[40:41], v[94:95]
	v_pk_mul_f32 v[36:37], v[36:37], v[210:211]
	v_pk_mul_f32 v[34:35], v[34:35], v[88:89]
	v_pk_mul_f32 v[30:31], v[30:31], v[92:93]
	v_pk_mul_f32 v[26:27], v[26:27], v[96:97]
	v_pk_mul_f32 v[22:23], v[22:23], v[212:213]
	v_pk_mul_f32 v[32:33], v[32:33], v[86:87]
	v_pk_mul_f32 v[28:29], v[28:29], v[90:91]
	v_pk_mul_f32 v[24:25], v[24:25], v[94:95]
	v_pk_mul_f32 v[20:21], v[20:21], v[210:211]
	v_pk_mul_f32 v[18:19], v[18:19], v[88:89]
	v_pk_mul_f32 v[14:15], v[14:15], v[92:93]
	v_pk_mul_f32 v[10:11], v[10:11], v[96:97]
	v_pk_mul_f32 v[6:7], v[6:7], v[212:213]
	v_pk_mul_f32 v[16:17], v[16:17], v[86:87]
	v_pk_mul_f32 v[12:13], v[12:13], v[90:91]
	v_pk_mul_f32 v[8:9], v[8:9], v[94:95]
	v_pk_mul_f32 v[4:5], v[4:5], v[210:211]
.LBB0_1140:
	s_xor_b32 s10, s55, 1
	s_lshl_b32 s11, s10, 14
	s_add_i32 s11, s11, 0
	v_add_u32_e32 v85, s11, v195
	s_lshl_b32 s10, s10, 13
	s_waitcnt vmcnt(0)
	s_waitcnt vmcnt(0)
	ds_write_b128 v85, v[164:167]
	v_add_u32_e32 v85, s11, v197
	s_add_i32 s11, s11, s10
	ds_write_b128 v85, v[160:163]
	v_add_u32_e32 v85, s11, v199
	ds_write_b128 v85, v[156:159] offset:32768
	ds_write_b128 v85, v[152:155] offset:45056
	v_add_u32_e32 v85, s11, v201
	ds_write_b128 v85, v[148:151] offset:32768
	v_lshl_add_u64 v[86:87], s[88:89], 0, v[178:179]
	v_lshl_add_u64 v[88:89], s[88:89], 0, v[176:177]
	global_load_dwordx4 v[164:167], v[86:87], off
	global_load_dwordx4 v[160:163], v[88:89], off
	v_lshl_add_u64 v[86:87], s[88:89], 0, v[170:171]
	v_lshl_add_u64 v[88:89], s[88:89], 0, v[172:173]
	global_load_dwordx4 v[156:159], v[86:87], off
	global_load_dwordx4 v[152:155], v[88:89], off
	v_lshl_add_u64 v[86:87], s[88:89], 0, v[174:175]
	global_load_dwordx4 v[148:151], v[86:87], off
	v_add_f32_e32 v2, v2, v84
	v_fmac_f32_e32 v2, v207, v208
	s_add_i32 s9, s9, 1
	v_lshl_add_u32 v96, s55, 14, v183
	ds_read_b64_tr_b16 v[84:85], v96 offset:0
	ds_read_b64_tr_b16 v[86:87], v96 offset:0x800
	ds_read_b64_tr_b16 v[88:89], v96 offset:0x1000
	ds_read_b64_tr_b16 v[90:91], v96 offset:0x1800
	ds_read_b64_tr_b16 v[208:209], v96 offset:0x2000
	ds_read_b64_tr_b16 v[210:211], v96 offset:0x2800
	ds_read_b64_tr_b16 v[92:93], v96 offset:0x3000
	ds_read_b64_tr_b16 v[94:95], v96 offset:0x3800
	ds_read_b64_tr_b16 v[212:213], v96 offset:0x200
	ds_read_b64_tr_b16 v[214:215], v96 offset:0xa00
	ds_read_b64_tr_b16 v[216:217], v96 offset:0x1200
	ds_read_b64_tr_b16 v[218:219], v96 offset:0x1a00
	ds_read_b64_tr_b16 v[220:221], v96 offset:0x2200
	ds_read_b64_tr_b16 v[222:223], v96 offset:0x2a00
	ds_read_b64_tr_b16 v[224:225], v96 offset:0x3200
	ds_read_b64_tr_b16 v[226:227], v96 offset:0x3a00
	ds_read_b64_tr_b16 v[228:229], v96 offset:0x400
	ds_read_b64_tr_b16 v[230:231], v96 offset:0xc00
	ds_read_b64_tr_b16 v[238:239], v96 offset:0x1400
	ds_read_b64_tr_b16 v[240:241], v96 offset:0x1c00
	ds_read_b64_tr_b16 v[242:243], v96 offset:0x2400
	ds_read_b64_tr_b16 v[244:245], v96 offset:0x2c00
	ds_read_b64_tr_b16 v[246:247], v96 offset:0x3400
	ds_read_b64_tr_b16 v[248:249], v96 offset:0x3c00
	ds_read_b64_tr_b16 v[250:251], v96 offset:0x600
	ds_read_b64_tr_b16 v[252:253], v96 offset:0xe00
	s_nop 0
	s_waitcnt lgkmcnt(15)
	v_mfma_f32_32x32x16_bf16 v[52:67], v[80:83], v[84:87], v[52:67]
	s_waitcnt lgkmcnt(15)
	v_mfma_f32_32x32x16_bf16 v[52:67], v[76:79], v[88:91], v[52:67]
	ds_read_b64_tr_b16 v[88:89], v96 offset:0x1600
	ds_read_b64_tr_b16 v[90:91], v96 offset:0x1e00
	s_waitcnt lgkmcnt(15)
	v_mfma_f32_32x32x16_bf16 v[52:67], v[68:71], v[208:211], v[52:67]
	s_waitcnt lgkmcnt(15)
	v_mfma_f32_32x32x16_bf16 v[52:67], v[72:75], v[92:95], v[52:67]
	s_waitcnt lgkmcnt(15)
	v_mfma_f32_32x32x16_bf16 v[36:51], v[80:83], v[212:215], v[36:51]
	s_waitcnt lgkmcnt(15)
	v_mfma_f32_32x32x16_bf16 v[36:51], v[76:79], v[216:219], v[36:51]
	s_waitcnt lgkmcnt(14)
	v_mfma_f32_32x32x16_bf16 v[36:51], v[68:71], v[220:223], v[36:51]
	s_waitcnt lgkmcnt(12)
	v_mfma_f32_32x32x16_bf16 v[36:51], v[72:75], v[224:227], v[36:51]
	s_waitcnt lgkmcnt(10)
	v_mfma_f32_32x32x16_bf16 v[20:35], v[80:83], v[228:231], v[20:35]
	s_waitcnt lgkmcnt(8)
	v_mfma_f32_32x32x16_bf16 v[20:35], v[76:79], v[238:241], v[20:35]
	s_waitcnt lgkmcnt(6)
	v_mfma_f32_32x32x16_bf16 v[20:35], v[68:71], v[242:245], v[20:35]
	s_waitcnt lgkmcnt(4)
	v_mfma_f32_32x32x16_bf16 v[20:35], v[72:75], v[246:249], v[20:35]
	s_waitcnt lgkmcnt(2)
	v_mfma_f32_32x32x16_bf16 v[4:19], v[80:83], v[250:253], v[4:19]
	ds_read_b64_tr_b16 v[80:81], v96 offset:0x2600
	ds_read_b64_tr_b16 v[82:83], v96 offset:0x2e00
	ds_read_b64_tr_b16 v[84:85], v96 offset:0x3600
	ds_read_b64_tr_b16 v[86:87], v96 offset:0x3e00
	s_waitcnt lgkmcnt(4)
	v_mfma_f32_32x32x16_bf16 v[4:19], v[76:79], v[88:91], v[4:19]
	s_waitcnt lgkmcnt(2)
	v_mfma_f32_32x32x16_bf16 v[4:19], v[68:71], v[80:83], v[4:19]
	v_lshl_add_u64 v[170:171], v[170:171], 0, s[2:3]
	v_lshl_add_u64 v[172:173], v[172:173], 0, s[2:3]
	v_lshl_add_u64 v[174:175], v[174:175], 0, s[2:3]
	v_lshl_add_u64 v[176:177], v[176:177], 0, s[4:5]
	v_lshl_add_u64 v[178:179], v[178:179], 0, s[4:5]
	s_cmp_eq_u32 s9, 22
	s_waitcnt lgkmcnt(0)
	v_mfma_f32_32x32x16_bf16 v[4:19], v[72:75], v[84:87], v[4:19]
	s_barrier
	s_cbranch_scc1 .LBB0_1142
	v_mov_b32_e32 v207, v2
	s_branch .LBB0_1136
.LBB0_1142:
	v_add_u32_e32 v206, 0, v206
	v_add_u32_e32 v207, v206, v189
	ds_read_b128 v[68:71], v207 offset:32768
	ds_read_b128 v[72:75], v207 offset:45056
	v_add_u32_e32 v201, 0, v205
	v_add_u32_e32 v208, v201, v189
	ds_read_b128 v[170:173], v208 offset:32768
	ds_read_b128 v[174:177], v208 offset:45056
	s_waitcnt lgkmcnt(3)
	v_mfma_f32_32x32x16_bf16 v[84:99], v[68:71], v[144:147], 0
	v_add_u32_e32 v204, 0, v204
	v_add_u32_e32 v205, v204, v189
	ds_read_b128 v[210:213], v205 offset:32768
	ds_read_b128 v[214:217], v205 offset:45056
	v_add_u32_e32 v197, 0, v203
	v_add_u32_e32 v203, v197, v189
	ds_read_b128 v[218:221], v203 offset:32768
	ds_read_b128 v[222:225], v203 offset:45056
	v_add_u32_e32 v199, 0, v202
	v_add_u32_e32 v202, v199, v189
	ds_read_b128 v[226:229], v202 offset:32768
	ds_read_b128 v[230:233], v202 offset:45056
	v_add_u32_e32 v179, 0, v200
	s_waitcnt lgkmcnt(8)
	v_mfma_f32_32x32x16_bf16 v[68:83], v[72:75], v[144:147], 0
	v_add_u32_e32 v200, v179, v189
	ds_read_b128 v[238:241], v200 offset:32768
	ds_read_b128 v[242:245], v200 offset:45056
	v_add_u32_e32 v195, 0, v198
	v_add_u32_e32 v198, v195, v189
	ds_read_b128 v[246:249], v198 offset:32768
	ds_read_b128 v[250:253], v198 offset:45056
	s_waitcnt lgkmcnt(11)
	v_mfma_f32_32x32x16_bf16 v[84:99], v[170:173], v[140:143], v[84:99]
	s_waitcnt lgkmcnt(10)
	v_mfma_f32_32x32x16_bf16 v[68:83], v[174:177], v[140:143], v[68:83]
	s_waitcnt lgkmcnt(9)
	v_mfma_f32_32x32x16_bf16 v[84:99], v[210:213], v[136:139], v[84:99]
	s_waitcnt lgkmcnt(8)
	v_mfma_f32_32x32x16_bf16 v[68:83], v[214:217], v[136:139], v[68:83]
	s_waitcnt lgkmcnt(7)
	v_mfma_f32_32x32x16_bf16 v[84:99], v[218:221], v[132:135], v[84:99]
	s_waitcnt lgkmcnt(6)
	v_mfma_f32_32x32x16_bf16 v[68:83], v[222:225], v[132:135], v[68:83]
	s_waitcnt lgkmcnt(5)
	v_mfma_f32_32x32x16_bf16 v[84:99], v[226:229], v[128:131], v[84:99]
	s_waitcnt lgkmcnt(4)
	v_mfma_f32_32x32x16_bf16 v[68:83], v[230:233], v[128:131], v[68:83]
	s_waitcnt lgkmcnt(3)
	v_mfma_f32_32x32x16_bf16 v[84:99], v[238:241], v[124:127], v[84:99]
	s_waitcnt lgkmcnt(2)
	v_mfma_f32_32x32x16_bf16 v[68:83], v[242:245], v[124:127], v[68:83]
	v_add_u32_e32 v176, 0, v196
	v_add_u32_e32 v196, v176, v189
	ds_read_b128 v[170:173], v196 offset:32768
	ds_read_b128 v[210:213], v196 offset:45056
	v_add_u32_e32 v177, 0, v194
	v_add_u32_e32 v194, v177, v189
	ds_read_b128 v[214:217], v194 offset:32768
	ds_read_b128 v[218:221], v194 offset:45056
	v_add_u32_e32 v175, 0, v193
	v_add_u32_e32 v193, v175, v189
	ds_read_b128 v[222:225], v193 offset:32768
	ds_read_b128 v[226:229], v193 offset:45056
	v_add_u32_e32 v174, 0, v191
	s_waitcnt lgkmcnt(7)
	v_mfma_f32_32x32x16_bf16 v[84:99], v[246:249], v[120:123], v[84:99]
	v_add_u32_e32 v191, v174, v189
	s_waitcnt lgkmcnt(6)
	v_mfma_f32_32x32x16_bf16 v[68:83], v[250:253], v[120:123], v[68:83]
	s_waitcnt lgkmcnt(5)
	v_mfma_f32_32x32x16_bf16 v[84:99], v[170:173], v[116:119], v[84:99]
	s_waitcnt lgkmcnt(4)
	v_mfma_f32_32x32x16_bf16 v[68:83], v[210:213], v[116:119], v[68:83]
	s_waitcnt lgkmcnt(3)
	v_mfma_f32_32x32x16_bf16 v[84:99], v[214:217], v[112:115], v[84:99]
	s_waitcnt lgkmcnt(2)
	v_mfma_f32_32x32x16_bf16 v[68:83], v[218:221], v[112:115], v[68:83]
	s_waitcnt lgkmcnt(1)
	v_mfma_f32_32x32x16_bf16 v[84:99], v[222:225], v[108:111], v[84:99]
	v_add_u32_e32 v173, 0, v192
	v_add_u32_e32 v192, v173, v189
	ds_read_b128 v[210:213], v192 offset:32768
	ds_read_b128 v[214:217], v192 offset:45056
	ds_read_b128 v[222:225], v191 offset:32768
	ds_read_b128 v[218:221], v191 offset:45056
	v_max_f32_e32 v172, v190, v190
	s_waitcnt lgkmcnt(4)
	v_mfma_f32_32x32x16_bf16 v[68:83], v[226:229], v[108:111], v[68:83]
	s_waitcnt lgkmcnt(3)
	v_mfma_f32_32x32x16_bf16 v[84:99], v[210:213], v[104:107], v[84:99]
	s_waitcnt lgkmcnt(1)
	v_mfma_f32_32x32x16_bf16 v[84:99], v[222:225], v[100:103], v[84:99]
	v_mfma_f32_32x32x16_bf16 v[68:83], v[214:217], v[104:107], v[68:83]
	s_nop 10
	v_max_f32_e32 v170, v85, v85
	v_max_f32_e32 v171, v84, v84
	v_max_f32_e32 v170, v171, v170
	v_max3_f32 v170, v170, v86, v87
	v_max3_f32 v170, v170, v88, v89
	v_max3_f32 v170, v170, v90, v91
	v_max3_f32 v170, v170, v92, v93
	s_waitcnt lgkmcnt(0)
	v_mfma_f32_32x32x16_bf16 v[68:83], v[218:221], v[100:103], v[68:83]
	v_max3_f32 v170, v170, v94, v95
	v_max3_f32 v170, v170, v96, v97
	v_max3_f32 v170, v170, v98, v99
	s_nop 8
	v_max3_f32 v170, v170, v68, v69
	v_max3_f32 v170, v170, v70, v71
	v_max3_f32 v170, v170, v72, v73
	v_max3_f32 v170, v170, v74, v75
	v_max3_f32 v170, v170, v76, v77
	v_max3_f32 v170, v170, v78, v79
	v_max3_f32 v170, v170, v80, v81
	v_max3_f32 v170, v170, v82, v83
	v_mov_b32_e32 v171, v170
	s_nop 1
	v_permlane32_swap_b32_e32 v170, v171
	v_max_f32_e32 v171, v171, v171
	v_max_f32_e32 v170, v170, v170
	v_max_f32_e32 v170, v170, v171
	v_sub_f32_e32 v171, v170, v190
	v_cmp_ge_f32_e32 vcc, s38, v171
	s_cmp_eq_u64 vcc, exec
	v_max_f32_e32 v172, v172, v170
	s_cselect_b64 vcc, -1, 0
	v_cndmask_b32_e32 v178, v172, v190, vcc
	v_mul_f32_e32 v171, 0xbdd53b94, v178
	v_fmamk_f32 v84, v84, 0x3dd53b94, v171
	v_fmamk_f32 v85, v85, 0x3dd53b94, v171
	v_fmamk_f32 v86, v86, 0x3dd53b94, v171
	v_fmamk_f32 v87, v87, 0x3dd53b94, v171
	v_fmamk_f32 v88, v88, 0x3dd53b94, v171
	v_fmamk_f32 v89, v89, 0x3dd53b94, v171
	v_fmamk_f32 v90, v90, 0x3dd53b94, v171
	v_fmamk_f32 v91, v91, 0x3dd53b94, v171
	v_fmamk_f32 v92, v92, 0x3dd53b94, v171
	v_fmamk_f32 v93, v93, 0x3dd53b94, v171
	v_fmamk_f32 v94, v94, 0x3dd53b94, v171
	v_fmamk_f32 v95, v95, 0x3dd53b94, v171
	v_fmamk_f32 v96, v96, 0x3dd53b94, v171
	v_fmamk_f32 v97, v97, 0x3dd53b94, v171
	v_fmamk_f32 v98, v98, 0x3dd53b94, v171
	v_fmamk_f32 v99, v99, 0x3dd53b94, v171
	v_fmamk_f32 v68, v68, 0x3dd53b94, v171
	v_fmamk_f32 v69, v69, 0x3dd53b94, v171
	v_fmamk_f32 v70, v70, 0x3dd53b94, v171
	v_fmamk_f32 v71, v71, 0x3dd53b94, v171
	v_fmamk_f32 v72, v72, 0x3dd53b94, v171
	v_fmamk_f32 v73, v73, 0x3dd53b94, v171
	v_fmamk_f32 v74, v74, 0x3dd53b94, v171
	v_fmamk_f32 v75, v75, 0x3dd53b94, v171
	v_fmamk_f32 v76, v76, 0x3dd53b94, v171
	v_fmamk_f32 v77, v77, 0x3dd53b94, v171
	v_fmamk_f32 v78, v78, 0x3dd53b94, v171
	v_fmamk_f32 v79, v79, 0x3dd53b94, v171
	v_fmamk_f32 v80, v80, 0x3dd53b94, v171
	v_fmamk_f32 v81, v81, 0x3dd53b94, v171
	v_fmamk_f32 v82, v82, 0x3dd53b94, v171
	v_fmac_f32_e32 v171, 0x3dd53b94, v83
	v_exp_f32_e32 v83, v84
	v_exp_f32_e32 v84, v85
	v_exp_f32_e32 v85, v86
	v_exp_f32_e32 v86, v87
	v_exp_f32_e32 v87, v88
	v_exp_f32_e32 v88, v89
	v_exp_f32_e32 v89, v90
	v_exp_f32_e32 v90, v91
	v_exp_f32_e32 v91, v92
	v_exp_f32_e32 v92, v93
	v_exp_f32_e32 v93, v94
	v_exp_f32_e32 v94, v95
	v_exp_f32_e32 v95, v96
	v_exp_f32_e32 v96, v97
	v_exp_f32_e32 v97, v98
	v_exp_f32_e32 v98, v99
	v_exp_f32_e32 v99, v68
	v_add_f32_e32 v68, 0, v83
	v_add_f32_e32 v68, v84, v68
	v_add_f32_e32 v68, v85, v68
	v_add_f32_e32 v68, v86, v68
	v_add_f32_e32 v68, v87, v68
	v_add_f32_e32 v68, v88, v68
	v_add_f32_e32 v68, v89, v68
	v_add_f32_e32 v68, v90, v68
	v_add_f32_e32 v68, v91, v68
	v_add_f32_e32 v68, v92, v68
	v_add_f32_e32 v68, v93, v68
	v_add_f32_e32 v68, v94, v68
	v_add_f32_e32 v68, v95, v68
	v_sub_f32_e32 v170, v190, v172
	v_exp_f32_e32 v190, v69
	v_add_f32_e32 v68, v96, v68
	v_exp_f32_e32 v209, v70
	v_add_f32_e32 v68, v97, v68
	v_exp_f32_e32 v210, v71
	v_add_f32_e32 v68, v98, v68
	v_exp_f32_e32 v211, v72
	v_add_f32_e32 v68, v99, v68
	v_exp_f32_e32 v212, v73
	v_add_f32_e32 v68, v190, v68
	v_exp_f32_e32 v213, v74
	v_add_f32_e32 v68, v209, v68
	v_exp_f32_e32 v214, v75
	v_add_f32_e32 v68, v210, v68
	v_exp_f32_e32 v76, v76
	v_add_f32_e32 v68, v211, v68
	v_exp_f32_e32 v77, v77
	v_add_f32_e32 v68, v212, v68
	v_exp_f32_e32 v78, v78
	v_add_f32_e32 v68, v213, v68
	v_exp_f32_e32 v79, v79
	v_add_f32_e32 v68, v214, v68
	v_exp_f32_e32 v215, v80
	v_add_f32_e32 v68, v76, v68
	v_exp_f32_e32 v216, v81
	v_add_f32_e32 v68, v77, v68
	v_exp_f32_e32 v217, v82
	v_add_f32_e32 v68, v78, v68
	v_exp_f32_e32 v218, v171
	v_add_f32_e32 v68, v79, v68
	v_mul_f32_e32 v170, 0x3dd53b94, v170
	v_add_f32_e32 v68, v215, v68
	v_exp_f32_e32 v170, v170
	v_add_f32_e32 v68, v216, v68
	v_add_f32_e32 v68, v217, v68
	v_add_f32_e32 v171, v218, v68
	v_mov_b32_e32 v172, v171
	v_cvt_pk_bf16_f32 v72, v83, v84
	v_cvt_pk_bf16_f32 v73, v85, v86
	v_cvt_pk_bf16_f32 v74, v87, v88
	v_cvt_pk_bf16_f32 v75, v89, v90
	v_cvt_pk_bf16_f32 v68, v91, v92
	v_cvt_pk_bf16_f32 v69, v93, v94
	v_cvt_pk_bf16_f32 v70, v95, v96
	v_cvt_pk_bf16_f32 v71, v97, v98
	v_cvt_pk_bf16_f32 v80, v99, v190
	v_cvt_pk_bf16_f32 v81, v209, v210
	v_cvt_pk_bf16_f32 v82, v211, v212
	v_cvt_pk_bf16_f32 v83, v213, v214
	v_cvt_pk_bf16_f32 v76, v76, v77
	v_cvt_pk_bf16_f32 v77, v78, v79
	v_cvt_pk_bf16_f32 v78, v215, v216
	v_cvt_pk_bf16_f32 v79, v217, v218
	v_cndmask_b32_e64 v170, v170, 1.0, vcc
	v_permlane32_swap_b32_e32 v171, v172
	v_permlane32_swap_b32_e32 v72, v74
	v_permlane32_swap_b32_e32 v73, v75
	v_permlane32_swap_b32_e32 v68, v70
	v_permlane32_swap_b32_e32 v69, v71
	v_permlane32_swap_b32_e32 v80, v82
	v_permlane32_swap_b32_e32 v81, v83
	v_permlane32_swap_b32_e32 v76, v78
	v_permlane32_swap_b32_e32 v77, v79
	v_cmp_gt_f32_e32 vcc, 1.0, v170
	s_cbranch_vccz .LBB0_1146
	s_and_saveexec_b64 s[10:11], s[0:1]
	ds_write_b32 v182, v170 offset:128
	s_or_b64 exec, exec, s[10:11]
	s_waitcnt lgkmcnt(0)
	ds_read_b128 v[84:87], v181 offset:224
	ds_read_b128 v[88:91], v181 offset:192
	ds_read_b128 v[92:95], v181 offset:160
	ds_read_b128 v[96:99], v181 offset:128
	s_waitcnt lgkmcnt(3)
	v_pk_mul_f32 v[66:67], v[66:67], v[86:87]
	s_waitcnt lgkmcnt(2)
	v_pk_mul_f32 v[62:63], v[62:63], v[90:91]
	s_waitcnt lgkmcnt(1)
	v_pk_mul_f32 v[58:59], v[58:59], v[94:95]
	s_waitcnt lgkmcnt(0)
	v_pk_mul_f32 v[54:55], v[54:55], v[98:99]
	v_pk_mul_f32 v[64:65], v[64:65], v[84:85]
	v_pk_mul_f32 v[60:61], v[60:61], v[88:89]
	v_pk_mul_f32 v[56:57], v[56:57], v[92:93]
	v_pk_mul_f32 v[52:53], v[52:53], v[96:97]
	v_pk_mul_f32 v[50:51], v[50:51], v[86:87]
	v_pk_mul_f32 v[46:47], v[46:47], v[90:91]
	v_pk_mul_f32 v[42:43], v[42:43], v[94:95]
	v_pk_mul_f32 v[38:39], v[38:39], v[98:99]
	v_pk_mul_f32 v[48:49], v[48:49], v[84:85]
	v_pk_mul_f32 v[44:45], v[44:45], v[88:89]
	v_pk_mul_f32 v[40:41], v[40:41], v[92:93]
	v_pk_mul_f32 v[36:37], v[36:37], v[96:97]
	v_pk_mul_f32 v[34:35], v[34:35], v[86:87]
	v_pk_mul_f32 v[30:31], v[30:31], v[90:91]
	v_pk_mul_f32 v[26:27], v[26:27], v[94:95]
	v_pk_mul_f32 v[22:23], v[22:23], v[98:99]
	v_pk_mul_f32 v[32:33], v[32:33], v[84:85]
	v_pk_mul_f32 v[28:29], v[28:29], v[88:89]
	v_pk_mul_f32 v[24:25], v[24:25], v[92:93]
	v_pk_mul_f32 v[20:21], v[20:21], v[96:97]
	v_pk_mul_f32 v[18:19], v[18:19], v[86:87]
	v_pk_mul_f32 v[14:15], v[14:15], v[90:91]
	v_pk_mul_f32 v[10:11], v[10:11], v[94:95]
	v_pk_mul_f32 v[6:7], v[6:7], v[98:99]
	v_pk_mul_f32 v[16:17], v[16:17], v[84:85]
	v_pk_mul_f32 v[12:13], v[12:13], v[88:89]
	v_pk_mul_f32 v[8:9], v[8:9], v[92:93]
	v_pk_mul_f32 v[4:5], v[4:5], v[96:97]
.LBB0_1146:
	ds_read_b64_tr_b16 v[84:85], v183 offset:0
	ds_read_b64_tr_b16 v[86:87], v183 offset:0x800
	ds_read_b64_tr_b16 v[88:89], v183 offset:0x1000
	ds_read_b64_tr_b16 v[90:91], v183 offset:0x1800
	ds_read_b64_tr_b16 v[96:97], v183 offset:0x2000
	ds_read_b64_tr_b16 v[98:99], v183 offset:0x2800
	ds_read_b64_tr_b16 v[92:93], v183 offset:0x3000
	ds_read_b64_tr_b16 v[94:95], v183 offset:0x3800
	ds_read_b64_tr_b16 v[212:213], v183 offset:0x200
	ds_read_b64_tr_b16 v[214:215], v183 offset:0xa00
	ds_read_b64_tr_b16 v[220:221], v183 offset:0x1200
	ds_read_b64_tr_b16 v[222:223], v183 offset:0x1a00
	ds_read_b64_tr_b16 v[224:225], v183 offset:0x2200
	ds_read_b64_tr_b16 v[226:227], v183 offset:0x2a00
	ds_read_b64_tr_b16 v[228:229], v183 offset:0x3200
	ds_read_b64_tr_b16 v[230:231], v183 offset:0x3a00
	ds_read_b64_tr_b16 v[238:239], v183 offset:0x400
	ds_read_b64_tr_b16 v[240:241], v183 offset:0xc00
	ds_read_b64_tr_b16 v[242:243], v183 offset:0x1400
	ds_read_b64_tr_b16 v[244:245], v183 offset:0x1c00
	ds_read_b64_tr_b16 v[246:247], v183 offset:0x2400
	ds_read_b64_tr_b16 v[248:249], v183 offset:0x2c00
	ds_read_b64_tr_b16 v[250:251], v183 offset:0x3400
	ds_read_b64_tr_b16 v[252:253], v183 offset:0x3c00
	s_waitcnt vmcnt(0)
	v_add_u32_e32 v189, 0x3000, v189
	s_waitcnt vmcnt(4)
	ds_write_b128 v184, v[164:167] offset:16384
	s_waitcnt vmcnt(3)
	ds_write_b128 v185, v[160:163] offset:16384
	s_waitcnt vmcnt(2)
	ds_write_b128 v186, v[156:159] offset:57344
	s_waitcnt vmcnt(1)
	ds_write_b128 v188, v[152:155] offset:57344
	s_waitcnt vmcnt(0)
	ds_write_b128 v187, v[148:151] offset:57344
	s_nop 0
	s_waitcnt lgkmcnt(15)
	v_mfma_f32_32x32x16_bf16 v[52:67], v[72:75], v[84:87], v[52:67]
	ds_read_b64_tr_b16 v[84:85], v183 offset:0x600
	ds_read_b64_tr_b16 v[86:87], v183 offset:0xe00
	ds_read_b64_tr_b16 v[148:149], v183 offset:0x1600
	ds_read_b64_tr_b16 v[150:151], v183 offset:0x1e00
	ds_read_b64_tr_b16 v[152:153], v183 offset:0x2600
	ds_read_b64_tr_b16 v[154:155], v183 offset:0x2e00
	ds_read_b64_tr_b16 v[156:157], v183 offset:0x3600
	ds_read_b64_tr_b16 v[158:159], v183 offset:0x3e00
	s_waitcnt lgkmcnt(15)
	v_mfma_f32_32x32x16_bf16 v[52:67], v[68:71], v[88:91], v[52:67]
	s_waitcnt lgkmcnt(15)
	v_mfma_f32_32x32x16_bf16 v[52:67], v[80:83], v[96:99], v[52:67]
	s_waitcnt lgkmcnt(15)
	v_mfma_f32_32x32x16_bf16 v[52:67], v[76:79], v[92:95], v[52:67]
	s_waitcnt lgkmcnt(15)
	v_mfma_f32_32x32x16_bf16 v[36:51], v[72:75], v[212:215], v[36:51]
	s_waitcnt lgkmcnt(15)
	v_mfma_f32_32x32x16_bf16 v[36:51], v[68:71], v[220:223], v[36:51]
	s_waitcnt lgkmcnt(15)
	v_mfma_f32_32x32x16_bf16 v[36:51], v[80:83], v[224:227], v[36:51]
	s_waitcnt lgkmcnt(15)
	v_mfma_f32_32x32x16_bf16 v[36:51], v[76:79], v[228:231], v[36:51]
	s_waitcnt lgkmcnt(15)
	v_mfma_f32_32x32x16_bf16 v[20:35], v[72:75], v[238:241], v[20:35]
	s_waitcnt lgkmcnt(15)
	v_mfma_f32_32x32x16_bf16 v[20:35], v[68:71], v[242:245], v[20:35]
	s_waitcnt lgkmcnt(15)
	v_mfma_f32_32x32x16_bf16 v[20:35], v[80:83], v[246:249], v[20:35]
	s_waitcnt lgkmcnt(13)
	v_mfma_f32_32x32x16_bf16 v[20:35], v[76:79], v[250:253], v[20:35]
	s_waitcnt lgkmcnt(6)
	v_mfma_f32_32x32x16_bf16 v[4:19], v[72:75], v[84:87], v[4:19]
	s_waitcnt lgkmcnt(4)
	v_mfma_f32_32x32x16_bf16 v[4:19], v[68:71], v[148:151], v[4:19]
	s_waitcnt lgkmcnt(2)
	v_mfma_f32_32x32x16_bf16 v[4:19], v[80:83], v[152:155], v[4:19]
	s_barrier
	ds_read_b128 v[68:71], v207 offset:57344
	ds_read_b128 v[148:151], v208 offset:57344
	s_waitcnt lgkmcnt(2)
	v_mfma_f32_32x32x16_bf16 v[4:19], v[76:79], v[156:159], v[4:19]
	v_add_u32_e32 v72, v206, v189
	s_waitcnt lgkmcnt(1)
	v_mfma_f32_32x32x16_bf16 v[84:99], v[68:71], v[144:147], 0
	ds_read_b128 v[68:71], v72 offset:57344
	v_add_u32_e32 v72, v201, v189
	ds_read_b128 v[152:155], v72 offset:57344
	ds_read_b128 v[156:159], v203 offset:57344
	ds_read_b128 v[164:167], v205 offset:57344
	s_waitcnt lgkmcnt(4)
	v_mfma_f32_32x32x16_bf16 v[84:99], v[148:151], v[140:143], v[84:99]
	v_add_u32_e32 v148, v204, v189
	ds_read_b128 v[204:207], v148 offset:57344
	s_waitcnt lgkmcnt(4)
	v_mfma_f32_32x32x16_bf16 v[68:83], v[68:71], v[144:147], 0
	s_waitcnt lgkmcnt(3)
	v_mfma_f32_32x32x16_bf16 v[68:83], v[152:155], v[140:143], v[68:83]
	s_waitcnt lgkmcnt(1)
	v_mfma_f32_32x32x16_bf16 v[84:99], v[164:167], v[136:139], v[84:99]
	v_add_u32_e32 v148, v197, v189
	ds_read_b128 v[148:151], v148 offset:57344
	ds_read_b128 v[144:147], v200 offset:57344
	ds_read_b128 v[164:167], v202 offset:57344
	s_waitcnt lgkmcnt(3)
	v_mfma_f32_32x32x16_bf16 v[68:83], v[204:207], v[136:139], v[68:83]
	v_add_u32_e32 v140, v199, v189
	ds_read_b128 v[136:139], v140 offset:57344
	v_mfma_f32_32x32x16_bf16 v[84:99], v[156:159], v[132:135], v[84:99]
	s_waitcnt lgkmcnt(3)
	v_mfma_f32_32x32x16_bf16 v[68:83], v[148:151], v[132:135], v[68:83]
	s_waitcnt lgkmcnt(1)
	v_mfma_f32_32x32x16_bf16 v[84:99], v[164:167], v[128:131], v[84:99]
	v_add_u32_e32 v140, v179, v189
	ds_read_b128 v[140:143], v140 offset:57344
	ds_read_b128 v[154:157], v196 offset:57344
	ds_read_b128 v[158:161], v198 offset:57344
	s_waitcnt lgkmcnt(3)
	v_mfma_f32_32x32x16_bf16 v[68:83], v[136:139], v[128:131], v[68:83]
	v_add_u32_e32 v132, v195, v189
	ds_read_b128 v[128:131], v132 offset:57344
	v_mfma_f32_32x32x16_bf16 v[84:99], v[144:147], v[124:127], v[84:99]
	s_waitcnt lgkmcnt(3)
	v_mfma_f32_32x32x16_bf16 v[68:83], v[140:143], v[124:127], v[68:83]
	s_waitcnt lgkmcnt(1)
	v_mfma_f32_32x32x16_bf16 v[84:99], v[158:161], v[120:123], v[84:99]
	v_add_u32_e32 v132, v176, v189
	ds_read_b128 v[132:135], v132 offset:57344
	ds_read_b128 v[136:139], v193 offset:57344
	ds_read_b128 v[140:143], v194 offset:57344
	s_waitcnt lgkmcnt(3)
	v_mfma_f32_32x32x16_bf16 v[68:83], v[128:131], v[120:123], v[68:83]
	v_add_u32_e32 v124, v177, v189
	ds_read_b128 v[120:123], v124 offset:57344
	v_mfma_f32_32x32x16_bf16 v[84:99], v[154:157], v[116:119], v[84:99]
	s_waitcnt lgkmcnt(3)
	v_mfma_f32_32x32x16_bf16 v[68:83], v[132:135], v[116:119], v[68:83]
	s_waitcnt lgkmcnt(1)
	v_mfma_f32_32x32x16_bf16 v[84:99], v[140:143], v[112:115], v[84:99]
	v_add_u32_e32 v124, v175, v189
	ds_read_b128 v[124:127], v124 offset:57344
	ds_read_b128 v[116:119], v192 offset:57344
	ds_read_b128 v[128:131], v191 offset:57344
	s_waitcnt lgkmcnt(3)
	v_mfma_f32_32x32x16_bf16 v[68:83], v[120:123], v[112:115], v[68:83]
	v_mfma_f32_32x32x16_bf16 v[84:99], v[136:139], v[108:111], v[84:99]
	s_waitcnt lgkmcnt(2)
	v_mfma_f32_32x32x16_bf16 v[68:83], v[124:127], v[108:111], v[68:83]
	s_waitcnt lgkmcnt(1)
	v_mfma_f32_32x32x16_bf16 v[84:99], v[116:119], v[104:107], v[84:99]
	v_add_u32_e32 v108, v173, v189
	ds_read_b128 v[108:111], v108 offset:57344
	s_waitcnt lgkmcnt(1)
	v_mfma_f32_32x32x16_bf16 v[84:99], v[128:131], v[100:103], v[84:99]
	v_add_u32_e32 v112, v174, v189
	ds_read_b128 v[112:115], v112 offset:57344
	s_waitcnt lgkmcnt(1)
	v_mfma_f32_32x32x16_bf16 v[68:83], v[108:111], v[104:107], v[68:83]
	s_nop 7
	v_max_f32_e32 v116, v85, v85
	v_max_f32_e32 v117, v84, v84
	v_max_f32_e32 v116, v117, v116
	v_max3_f32 v104, v116, v86, v87
	v_max3_f32 v104, v104, v88, v89
	v_max3_f32 v104, v104, v90, v91
	v_max3_f32 v104, v104, v92, v93
	s_waitcnt lgkmcnt(0)
	v_mfma_f32_32x32x16_bf16 v[68:83], v[112:115], v[100:103], v[68:83]
	v_max3_f32 v104, v104, v94, v95
	v_max3_f32 v104, v104, v96, v97
	v_max3_f32 v104, v104, v98, v99
	v_max_f32_e32 v102, v178, v178
	s_nop 7
	v_max3_f32 v100, v104, v68, v69
	v_max3_f32 v100, v100, v70, v71
	v_max3_f32 v100, v100, v72, v73
	v_max3_f32 v100, v100, v74, v75
	v_max3_f32 v100, v100, v76, v77
	v_max3_f32 v100, v100, v78, v79
	v_max3_f32 v100, v100, v80, v81
	v_max3_f32 v100, v100, v82, v83
	v_mov_b32_e32 v101, v100
	s_nop 1
	v_permlane32_swap_b32_e32 v100, v101
	v_max_f32_e32 v101, v101, v101
	v_max_f32_e32 v100, v100, v100
	v_max_f32_e32 v100, v100, v101
	v_sub_f32_e32 v101, v100, v178
	v_cmp_ge_f32_e32 vcc, s38, v101
	s_cmp_eq_u64 vcc, exec
	v_max_f32_e32 v102, v102, v100
	s_cselect_b64 vcc, -1, 0
	v_cndmask_b32_e32 v101, v102, v178, vcc
	v_mul_f32_e32 v101, 0xbdd53b94, v101
	v_fmamk_f32 v84, v84, 0x3dd53b94, v101
	v_fmamk_f32 v85, v85, 0x3dd53b94, v101
	v_fmamk_f32 v86, v86, 0x3dd53b94, v101
	v_fmamk_f32 v87, v87, 0x3dd53b94, v101
	v_fmamk_f32 v88, v88, 0x3dd53b94, v101
	v_fmamk_f32 v89, v89, 0x3dd53b94, v101
	v_fmamk_f32 v90, v90, 0x3dd53b94, v101
	v_fmamk_f32 v91, v91, 0x3dd53b94, v101
	v_fmamk_f32 v92, v92, 0x3dd53b94, v101
	v_fmamk_f32 v93, v93, 0x3dd53b94, v101
	v_fmamk_f32 v94, v94, 0x3dd53b94, v101
	v_fmamk_f32 v95, v95, 0x3dd53b94, v101
	v_fmamk_f32 v96, v96, 0x3dd53b94, v101
	v_fmamk_f32 v97, v97, 0x3dd53b94, v101
	v_fmamk_f32 v98, v98, 0x3dd53b94, v101
	v_fmamk_f32 v99, v99, 0x3dd53b94, v101
	v_fmamk_f32 v68, v68, 0x3dd53b94, v101
	v_fmamk_f32 v69, v69, 0x3dd53b94, v101
	v_fmamk_f32 v70, v70, 0x3dd53b94, v101
	v_fmamk_f32 v71, v71, 0x3dd53b94, v101
	v_fmamk_f32 v72, v72, 0x3dd53b94, v101
	v_fmamk_f32 v73, v73, 0x3dd53b94, v101
	v_fmamk_f32 v74, v74, 0x3dd53b94, v101
	v_fmamk_f32 v75, v75, 0x3dd53b94, v101
	v_fmamk_f32 v76, v76, 0x3dd53b94, v101
	v_fmamk_f32 v77, v77, 0x3dd53b94, v101
	v_fmamk_f32 v78, v78, 0x3dd53b94, v101
	v_fmamk_f32 v79, v79, 0x3dd53b94, v101
	v_fmamk_f32 v80, v80, 0x3dd53b94, v101
	v_fmamk_f32 v81, v81, 0x3dd53b94, v101
	v_fmamk_f32 v82, v82, 0x3dd53b94, v101
	v_fmac_f32_e32 v101, 0x3dd53b94, v83
	v_exp_f32_e32 v83, v84
	v_sub_f32_e32 v100, v178, v102
	v_exp_f32_e32 v102, v85
	v_exp_f32_e32 v86, v86
	v_exp_f32_e32 v87, v87
	v_exp_f32_e32 v88, v88
	v_exp_f32_e32 v103, v68
	v_add_f32_e32 v68, 0, v83
	v_exp_f32_e32 v89, v89
	v_add_f32_e32 v68, v102, v68
	v_exp_f32_e32 v90, v90
	v_add_f32_e32 v68, v86, v68
	v_exp_f32_e32 v91, v91
	v_add_f32_e32 v68, v87, v68
	v_exp_f32_e32 v92, v92
	v_add_f32_e32 v68, v88, v68
	v_exp_f32_e32 v93, v93
	v_add_f32_e32 v68, v89, v68
	v_exp_f32_e32 v94, v94
	v_add_f32_e32 v68, v90, v68
	v_exp_f32_e32 v95, v95
	v_add_f32_e32 v68, v91, v68
	v_exp_f32_e32 v96, v96
	v_add_f32_e32 v68, v92, v68
	v_exp_f32_e32 v97, v97
	v_add_f32_e32 v68, v93, v68
	v_exp_f32_e32 v98, v98
	v_add_f32_e32 v68, v94, v68
	v_exp_f32_e32 v99, v99
	v_add_f32_e32 v68, v95, v68
	v_add_f32_e32 v68, v96, v68
	v_exp_f32_e32 v104, v69
	v_add_f32_e32 v68, v97, v68
	v_exp_f32_e32 v105, v70
	v_add_f32_e32 v68, v98, v68
	v_exp_f32_e32 v106, v71
	v_add_f32_e32 v68, v99, v68
	v_exp_f32_e32 v107, v72
	v_add_f32_e32 v68, v103, v68
	v_exp_f32_e32 v108, v73
	v_add_f32_e32 v68, v104, v68
	v_exp_f32_e32 v109, v74
	v_add_f32_e32 v68, v105, v68
	v_exp_f32_e32 v110, v75
	v_add_f32_e32 v68, v106, v68
	v_exp_f32_e32 v76, v76
	v_add_f32_e32 v68, v107, v68
	v_exp_f32_e32 v77, v77
	v_add_f32_e32 v68, v108, v68
	v_exp_f32_e32 v78, v78
	v_add_f32_e32 v68, v109, v68
	v_exp_f32_e32 v79, v79
	v_add_f32_e32 v68, v110, v68
	v_exp_f32_e32 v111, v80
	v_add_f32_e32 v68, v76, v68
	v_exp_f32_e32 v112, v81
	v_add_f32_e32 v68, v77, v68
	v_exp_f32_e32 v113, v82
	v_add_f32_e32 v68, v78, v68
	v_exp_f32_e32 v101, v101
	v_add_f32_e32 v68, v79, v68
	v_mul_f32_e32 v100, 0x3dd53b94, v100
	v_add_f32_e32 v68, v111, v68
	v_exp_f32_e32 v100, v100
	v_add_f32_e32 v68, v112, v68
	v_add_f32_e32 v68, v113, v68
	v_add_f32_e32 v84, v101, v68
	v_mov_b32_e32 v85, v84
	v_cvt_pk_bf16_f32 v72, v83, v102
	v_cvt_pk_bf16_f32 v73, v86, v87
	v_cvt_pk_bf16_f32 v74, v88, v89
	v_cvt_pk_bf16_f32 v75, v90, v91
	v_cvt_pk_bf16_f32 v68, v92, v93
	v_cvt_pk_bf16_f32 v69, v94, v95
	v_cvt_pk_bf16_f32 v70, v96, v97
	v_cvt_pk_bf16_f32 v71, v98, v99
	v_cvt_pk_bf16_f32 v80, v103, v104
	v_cvt_pk_bf16_f32 v81, v105, v106
	v_cvt_pk_bf16_f32 v82, v107, v108
	v_cvt_pk_bf16_f32 v83, v109, v110
	v_cvt_pk_bf16_f32 v76, v76, v77
	v_cvt_pk_bf16_f32 v77, v78, v79
	v_cvt_pk_bf16_f32 v78, v111, v112
	v_cvt_pk_bf16_f32 v79, v113, v101
	v_cndmask_b32_e64 v100, v100, 1.0, vcc
	v_permlane32_swap_b32_e32 v84, v85
	v_permlane32_swap_b32_e32 v72, v74
	v_permlane32_swap_b32_e32 v73, v75
	v_permlane32_swap_b32_e32 v68, v70
	v_permlane32_swap_b32_e32 v69, v71
	v_permlane32_swap_b32_e32 v80, v82
	v_permlane32_swap_b32_e32 v81, v83
	v_permlane32_swap_b32_e32 v76, v78
	v_permlane32_swap_b32_e32 v77, v79
	v_cmp_gt_f32_e32 vcc, 1.0, v100
	s_cbranch_vccz .LBB0_1150
	s_and_saveexec_b64 s[10:11], s[0:1]
	ds_write_b32 v182, v100 offset:128
	s_or_b64 exec, exec, s[10:11]
	s_waitcnt lgkmcnt(0)
	ds_read_b128 v[86:89], v181 offset:224
	ds_read_b128 v[90:93], v181 offset:192
	ds_read_b128 v[94:97], v181 offset:160
	ds_read_b128 v[102:105], v181 offset:128
	s_waitcnt lgkmcnt(3)
	v_pk_mul_f32 v[66:67], v[66:67], v[88:89]
	s_waitcnt lgkmcnt(2)
	v_pk_mul_f32 v[62:63], v[62:63], v[92:93]
	s_waitcnt lgkmcnt(1)
	v_pk_mul_f32 v[58:59], v[58:59], v[96:97]
	s_waitcnt lgkmcnt(0)
	v_pk_mul_f32 v[54:55], v[54:55], v[104:105]
	v_pk_mul_f32 v[64:65], v[64:65], v[86:87]
	v_pk_mul_f32 v[60:61], v[60:61], v[90:91]
	v_pk_mul_f32 v[56:57], v[56:57], v[94:95]
	v_pk_mul_f32 v[52:53], v[52:53], v[102:103]
	v_pk_mul_f32 v[50:51], v[50:51], v[88:89]
	v_pk_mul_f32 v[46:47], v[46:47], v[92:93]
	v_pk_mul_f32 v[42:43], v[42:43], v[96:97]
	v_pk_mul_f32 v[38:39], v[38:39], v[104:105]
	v_pk_mul_f32 v[48:49], v[48:49], v[86:87]
	v_pk_mul_f32 v[44:45], v[44:45], v[90:91]
	v_pk_mul_f32 v[40:41], v[40:41], v[94:95]
	v_pk_mul_f32 v[36:37], v[36:37], v[102:103]
	v_pk_mul_f32 v[34:35], v[34:35], v[88:89]
	v_pk_mul_f32 v[30:31], v[30:31], v[92:93]
	v_pk_mul_f32 v[26:27], v[26:27], v[96:97]
	v_pk_mul_f32 v[22:23], v[22:23], v[104:105]
	v_pk_mul_f32 v[32:33], v[32:33], v[86:87]
	v_pk_mul_f32 v[28:29], v[28:29], v[90:91]
	v_pk_mul_f32 v[24:25], v[24:25], v[94:95]
	v_pk_mul_f32 v[20:21], v[20:21], v[102:103]
	v_pk_mul_f32 v[18:19], v[18:19], v[88:89]
	v_pk_mul_f32 v[14:15], v[14:15], v[92:93]
	v_pk_mul_f32 v[10:11], v[10:11], v[96:97]
	v_pk_mul_f32 v[6:7], v[6:7], v[104:105]
	v_pk_mul_f32 v[16:17], v[16:17], v[86:87]
	v_pk_mul_f32 v[12:13], v[12:13], v[90:91]
	v_pk_mul_f32 v[8:9], v[8:9], v[94:95]
	v_pk_mul_f32 v[4:5], v[4:5], v[102:103]
.LBB0_1150:
	v_add_u32_e32 v98, 0x4000, v183
	ds_read_b64_tr_b16 v[86:87], v98 offset:0
	ds_read_b64_tr_b16 v[88:89], v98 offset:0x800
	ds_read_b64_tr_b16 v[90:91], v98 offset:0x1000
	ds_read_b64_tr_b16 v[92:93], v98 offset:0x1800
	ds_read_b64_tr_b16 v[102:103], v98 offset:0x2000
	ds_read_b64_tr_b16 v[104:105], v98 offset:0x2800
	ds_read_b64_tr_b16 v[94:95], v98 offset:0x3000
	ds_read_b64_tr_b16 v[96:97], v98 offset:0x3800
	ds_read_b64_tr_b16 v[110:111], v98 offset:0x200
	ds_read_b64_tr_b16 v[112:113], v98 offset:0xa00
	ds_read_b64_tr_b16 v[118:119], v98 offset:0x1200
	ds_read_b64_tr_b16 v[120:121], v98 offset:0x1a00
	ds_read_b64_tr_b16 v[122:123], v98 offset:0x2200
	ds_read_b64_tr_b16 v[124:125], v98 offset:0x2a00
	ds_read_b64_tr_b16 v[126:127], v98 offset:0x3200
	ds_read_b64_tr_b16 v[128:129], v98 offset:0x3a00
	ds_read_b64_tr_b16 v[130:131], v98 offset:0x400
	ds_read_b64_tr_b16 v[132:133], v98 offset:0xc00
	ds_read_b64_tr_b16 v[134:135], v98 offset:0x1400
	ds_read_b64_tr_b16 v[136:137], v98 offset:0x1c00
	ds_read_b64_tr_b16 v[138:139], v98 offset:0x2400
	ds_read_b64_tr_b16 v[140:141], v98 offset:0x2c00
	ds_read_b64_tr_b16 v[142:143], v98 offset:0x3400
	ds_read_b64_tr_b16 v[144:145], v98 offset:0x3c00
	ds_read_b64_tr_b16 v[146:147], v98 offset:0x600
	ds_read_b64_tr_b16 v[148:149], v98 offset:0xe00
	s_nop 0
	s_waitcnt lgkmcnt(15)
	v_mfma_f32_32x32x16_bf16 v[52:67], v[72:75], v[86:89], v[52:67]
	s_waitcnt lgkmcnt(15)
	v_mfma_f32_32x32x16_bf16 v[52:67], v[68:71], v[90:93], v[52:67]
	ds_read_b64_tr_b16 v[90:91], v98 offset:0x1600
	ds_read_b64_tr_b16 v[92:93], v98 offset:0x1e00
	ds_read_b64_tr_b16 v[154:155], v98 offset:0x2600
	ds_read_b64_tr_b16 v[156:157], v98 offset:0x2e00
	ds_read_b64_tr_b16 v[86:87], v98 offset:0x3600
	ds_read_b64_tr_b16 v[88:89], v98 offset:0x3e00
	s_waitcnt lgkmcnt(15)
	v_mfma_f32_32x32x16_bf16 v[52:67], v[80:83], v[102:105], v[52:67]
	s_waitcnt lgkmcnt(15)
	v_mfma_f32_32x32x16_bf16 v[52:67], v[76:79], v[94:97], v[52:67]
	s_waitcnt lgkmcnt(15)
	v_mfma_f32_32x32x16_bf16 v[36:51], v[72:75], v[110:113], v[36:51]
	s_waitcnt lgkmcnt(15)
	v_mfma_f32_32x32x16_bf16 v[36:51], v[68:71], v[118:121], v[36:51]
	s_waitcnt lgkmcnt(15)
	v_mfma_f32_32x32x16_bf16 v[36:51], v[80:83], v[122:125], v[36:51]
	s_waitcnt lgkmcnt(15)
	v_mfma_f32_32x32x16_bf16 v[36:51], v[76:79], v[126:129], v[36:51]
	s_waitcnt lgkmcnt(14)
	v_mfma_f32_32x32x16_bf16 v[20:35], v[72:75], v[130:133], v[20:35]
	s_waitcnt lgkmcnt(12)
	v_mfma_f32_32x32x16_bf16 v[20:35], v[68:71], v[134:137], v[20:35]
	s_waitcnt lgkmcnt(10)
	v_mfma_f32_32x32x16_bf16 v[20:35], v[80:83], v[138:141], v[20:35]
	s_waitcnt lgkmcnt(8)
	v_mfma_f32_32x32x16_bf16 v[20:35], v[76:79], v[142:145], v[20:35]
	s_waitcnt lgkmcnt(6)
	v_mfma_f32_32x32x16_bf16 v[4:19], v[72:75], v[146:149], v[4:19]
	s_waitcnt lgkmcnt(4)
	v_mfma_f32_32x32x16_bf16 v[4:19], v[68:71], v[90:93], v[4:19]
	s_waitcnt lgkmcnt(2)
	v_mfma_f32_32x32x16_bf16 v[4:19], v[80:83], v[154:157], v[4:19]
	s_barrier
	s_waitcnt lgkmcnt(0)
	v_mfma_f32_32x32x16_bf16 v[4:19], v[76:79], v[86:89], v[4:19]
	s_and_saveexec_b64 s[10:11], s[0:1]
	s_cbranch_execz .LBB0_1134
	v_add_f32_e32 v68, v171, v172
	v_fmac_f32_e32 v68, v2, v170
	v_add_f32_e32 v2, v84, v85
	v_fmac_f32_e32 v2, v68, v100
	ds_write_b32 v182, v2
	s_branch .LBB0_1134

.LBB0_1156:
	v_add_u32_e32 v2, s12, v221
	ds_read_b128 v[68:71], v2
	ds_read_b128 v[72:75], v2 offset:12288
	v_add_u32_e32 v2, s12, v220
	ds_read_b128 v[224:227], v2
	ds_read_b128 v[228:231], v2 offset:12288
	v_add_u32_e32 v2, s12, v219
	ds_read_b128 v[238:241], v2
	ds_read_b128 v[242:245], v2 offset:12288
	s_waitcnt vmcnt(16)
	s_waitcnt lgkmcnt(5)
	v_mfma_f32_32x32x16_bf16 v[84:99], v[68:71], v[144:147], 0
	s_waitcnt lgkmcnt(4)
	v_mfma_f32_32x32x16_bf16 v[68:83], v[72:75], v[144:147], 0
	s_waitcnt vmcnt(15)
	s_waitcnt lgkmcnt(3)
	v_mfma_f32_32x32x16_bf16 v[84:99], v[224:227], v[140:143], v[84:99]
	s_waitcnt lgkmcnt(2)
	v_mfma_f32_32x32x16_bf16 v[68:83], v[228:231], v[140:143], v[68:83]
	v_add_u32_e32 v2, s12, v218
	ds_read_b128 v[224:227], v2
	ds_read_b128 v[228:231], v2 offset:12288
	s_waitcnt vmcnt(14)
	s_waitcnt lgkmcnt(3)
	v_mfma_f32_32x32x16_bf16 v[84:99], v[238:241], v[136:139], v[84:99]
	s_waitcnt lgkmcnt(2)
	v_mfma_f32_32x32x16_bf16 v[68:83], v[242:245], v[136:139], v[68:83]
	v_add_u32_e32 v2, s12, v217
	ds_read_b128 v[238:241], v2
	ds_read_b128 v[242:245], v2 offset:12288
	s_waitcnt vmcnt(13)
	s_waitcnt lgkmcnt(3)
	v_mfma_f32_32x32x16_bf16 v[84:99], v[224:227], v[132:135], v[84:99]
	s_waitcnt lgkmcnt(2)
	v_mfma_f32_32x32x16_bf16 v[68:83], v[228:231], v[132:135], v[68:83]
	v_add_u32_e32 v2, s12, v216
	ds_read_b128 v[224:227], v2
	ds_read_b128 v[228:231], v2 offset:12288
	s_waitcnt vmcnt(12)
	s_waitcnt lgkmcnt(3)
	v_mfma_f32_32x32x16_bf16 v[84:99], v[238:241], v[128:131], v[84:99]
	s_waitcnt lgkmcnt(2)
	v_mfma_f32_32x32x16_bf16 v[68:83], v[242:245], v[128:131], v[68:83]
	v_add_u32_e32 v2, s12, v215
	ds_read_b128 v[238:241], v2
	ds_read_b128 v[242:245], v2 offset:12288
	s_waitcnt vmcnt(11)
	s_waitcnt lgkmcnt(3)
	v_mfma_f32_32x32x16_bf16 v[84:99], v[224:227], v[124:127], v[84:99]
	s_waitcnt lgkmcnt(2)
	v_mfma_f32_32x32x16_bf16 v[68:83], v[228:231], v[124:127], v[68:83]
	v_add_u32_e32 v2, s12, v214
	ds_read_b128 v[224:227], v2
	ds_read_b128 v[228:231], v2 offset:12288
	s_waitcnt vmcnt(10)
	s_waitcnt lgkmcnt(3)
	v_mfma_f32_32x32x16_bf16 v[84:99], v[238:241], v[120:123], v[84:99]
	s_waitcnt lgkmcnt(2)
	v_mfma_f32_32x32x16_bf16 v[68:83], v[242:245], v[120:123], v[68:83]
	v_add_u32_e32 v2, s12, v213
	ds_read_b128 v[238:241], v2
	ds_read_b128 v[242:245], v2 offset:12288
	s_waitcnt vmcnt(9)
	s_waitcnt lgkmcnt(3)
	v_mfma_f32_32x32x16_bf16 v[84:99], v[224:227], v[116:119], v[84:99]
	s_waitcnt lgkmcnt(2)
	v_mfma_f32_32x32x16_bf16 v[68:83], v[228:231], v[116:119], v[68:83]
	v_add_u32_e32 v2, s12, v212
	ds_read_b128 v[224:227], v2
	ds_read_b128 v[228:231], v2 offset:12288
	s_waitcnt vmcnt(8)
	s_waitcnt lgkmcnt(3)
	v_mfma_f32_32x32x16_bf16 v[84:99], v[238:241], v[112:115], v[84:99]
	s_waitcnt lgkmcnt(2)
	v_mfma_f32_32x32x16_bf16 v[68:83], v[242:245], v[112:115], v[68:83]
	v_add_u32_e32 v2, s12, v211
	ds_read_b128 v[238:241], v2
	ds_read_b128 v[242:245], v2 offset:12288
	s_waitcnt vmcnt(7)
	s_waitcnt lgkmcnt(3)
	v_mfma_f32_32x32x16_bf16 v[84:99], v[224:227], v[108:111], v[84:99]
	s_waitcnt lgkmcnt(2)
	v_mfma_f32_32x32x16_bf16 v[68:83], v[228:231], v[108:111], v[68:83]
	v_add_u32_e32 v2, s12, v210
	ds_read_b128 v[224:227], v2
	ds_read_b128 v[232:235], v2 offset:12288
	s_waitcnt vmcnt(6)
	s_waitcnt lgkmcnt(3)
	v_mfma_f32_32x32x16_bf16 v[84:99], v[238:241], v[104:107], v[84:99]
	s_waitcnt vmcnt(5)
	s_waitcnt lgkmcnt(1)
	v_mfma_f32_32x32x16_bf16 v[84:99], v[224:227], v[100:103], v[84:99]
	v_max_f32_e32 v224, v193, v193
	v_mfma_f32_32x32x16_bf16 v[68:83], v[242:245], v[104:107], v[68:83]
	s_nop 9
	v_max_f32_e32 v2, v85, v85
	v_max_f32_e32 v223, v84, v84
	v_max_f32_e32 v2, v223, v2
	v_max3_f32 v2, v2, v86, v87
	v_max3_f32 v2, v2, v88, v89
	v_max3_f32 v2, v2, v90, v91
	v_max3_f32 v2, v2, v92, v93
	s_waitcnt lgkmcnt(0)
	v_mfma_f32_32x32x16_bf16 v[68:83], v[232:235], v[100:103], v[68:83]
	v_max3_f32 v2, v2, v94, v95
	v_max3_f32 v2, v2, v96, v97
	v_max3_f32 v2, v2, v98, v99
	s_nop 8
	v_max3_f32 v2, v2, v68, v69
	v_max3_f32 v2, v2, v70, v71
	v_max3_f32 v2, v2, v72, v73
	v_max3_f32 v2, v2, v74, v75
	v_max3_f32 v2, v2, v76, v77
	v_max3_f32 v2, v2, v78, v79
	v_max3_f32 v2, v2, v80, v81
	v_max3_f32 v2, v2, v82, v83
	v_mov_b32_e32 v223, v2
	s_nop 1
	v_permlane32_swap_b32_e32 v2, v223
	v_max_f32_e32 v223, v223, v223
	v_max_f32_e32 v2, v2, v2
	v_max_f32_e32 v2, v2, v223
	v_sub_f32_e32 v223, v2, v193
	v_cmp_ge_f32_e32 vcc, s43, v223
	s_cmp_eq_u64 vcc, exec
	v_max_f32_e32 v2, v224, v2
	s_cselect_b64 vcc, -1, 0
	v_sub_f32_e32 v224, v193, v2
	v_cndmask_b32_e32 v193, v2, v193, vcc
	v_mul_f32_e32 v2, 0xbdd53b94, v193
	v_fmamk_f32 v84, v84, 0x3dd53b94, v2
	v_fmamk_f32 v85, v85, 0x3dd53b94, v2
	v_fmamk_f32 v86, v86, 0x3dd53b94, v2
	v_fmamk_f32 v87, v87, 0x3dd53b94, v2
	v_fmamk_f32 v88, v88, 0x3dd53b94, v2
	v_fmamk_f32 v89, v89, 0x3dd53b94, v2
	v_fmamk_f32 v90, v90, 0x3dd53b94, v2
	v_fmamk_f32 v91, v91, 0x3dd53b94, v2
	v_fmamk_f32 v92, v92, 0x3dd53b94, v2
	v_fmamk_f32 v93, v93, 0x3dd53b94, v2
	v_fmamk_f32 v94, v94, 0x3dd53b94, v2
	v_fmamk_f32 v95, v95, 0x3dd53b94, v2
	v_fmamk_f32 v96, v96, 0x3dd53b94, v2
	v_fmamk_f32 v97, v97, 0x3dd53b94, v2
	v_fmamk_f32 v98, v98, 0x3dd53b94, v2
	v_fmamk_f32 v99, v99, 0x3dd53b94, v2
	v_fmamk_f32 v68, v68, 0x3dd53b94, v2
	v_fmamk_f32 v69, v69, 0x3dd53b94, v2
	v_fmamk_f32 v70, v70, 0x3dd53b94, v2
	v_fmamk_f32 v71, v71, 0x3dd53b94, v2
	v_fmamk_f32 v72, v72, 0x3dd53b94, v2
	v_fmamk_f32 v73, v73, 0x3dd53b94, v2
	v_fmamk_f32 v74, v74, 0x3dd53b94, v2
	v_fmamk_f32 v75, v75, 0x3dd53b94, v2
	v_fmamk_f32 v76, v76, 0x3dd53b94, v2
	v_fmamk_f32 v77, v77, 0x3dd53b94, v2
	v_fmamk_f32 v78, v78, 0x3dd53b94, v2
	v_fmamk_f32 v79, v79, 0x3dd53b94, v2
	v_fmamk_f32 v80, v80, 0x3dd53b94, v2
	v_fmamk_f32 v81, v81, 0x3dd53b94, v2
	v_fmamk_f32 v82, v82, 0x3dd53b94, v2
	v_fmac_f32_e32 v2, 0x3dd53b94, v83
	v_exp_f32_e32 v83, v84
	v_exp_f32_e32 v85, v85
	v_exp_f32_e32 v86, v86
	v_exp_f32_e32 v87, v87
	v_exp_f32_e32 v88, v88
	v_exp_f32_e32 v231, v2
	v_add_f32_e32 v2, 0, v83
	v_exp_f32_e32 v89, v89
	v_add_f32_e32 v2, v85, v2
	v_exp_f32_e32 v90, v90
	v_add_f32_e32 v2, v86, v2
	v_exp_f32_e32 v91, v91
	v_add_f32_e32 v2, v87, v2
	v_exp_f32_e32 v92, v92
	v_add_f32_e32 v2, v88, v2
	v_exp_f32_e32 v93, v93
	v_add_f32_e32 v2, v89, v2
	v_exp_f32_e32 v94, v94
	v_add_f32_e32 v2, v90, v2
	v_exp_f32_e32 v95, v95
	v_add_f32_e32 v2, v91, v2
	v_exp_f32_e32 v96, v96
	v_add_f32_e32 v2, v92, v2
	v_exp_f32_e32 v97, v97
	v_add_f32_e32 v2, v93, v2
	v_exp_f32_e32 v98, v98
	v_add_f32_e32 v2, v94, v2
	v_exp_f32_e32 v99, v99
	v_add_f32_e32 v2, v95, v2
	v_exp_f32_e32 v68, v68
	v_add_f32_e32 v2, v96, v2
	v_exp_f32_e32 v69, v69
	v_add_f32_e32 v2, v97, v2
	v_exp_f32_e32 v70, v70
	v_add_f32_e32 v2, v98, v2
	v_mul_f32_e32 v224, 0x3dd53b94, v224
	v_exp_f32_e32 v71, v71
	v_add_f32_e32 v2, v99, v2
	v_exp_f32_e32 v224, v224
	v_exp_f32_e32 v72, v72
	v_add_f32_e32 v2, v68, v2
	v_exp_f32_e32 v73, v73
	v_add_f32_e32 v2, v69, v2
	v_exp_f32_e32 v74, v74
	v_add_f32_e32 v2, v70, v2
	v_exp_f32_e32 v75, v75
	v_add_f32_e32 v2, v71, v2
	v_cndmask_b32_e64 v223, v224, 1.0, vcc
	v_exp_f32_e32 v224, v76
	v_add_f32_e32 v2, v72, v2
	v_exp_f32_e32 v225, v77
	v_add_f32_e32 v2, v73, v2
	v_exp_f32_e32 v226, v78
	v_add_f32_e32 v2, v74, v2
	v_exp_f32_e32 v227, v79
	v_add_f32_e32 v2, v75, v2
	v_exp_f32_e32 v228, v80
	v_add_f32_e32 v2, v224, v2
	v_exp_f32_e32 v229, v81
	v_add_f32_e32 v2, v225, v2
	v_exp_f32_e32 v230, v82
	v_add_f32_e32 v2, v226, v2
	v_add_f32_e32 v2, v227, v2
	v_add_f32_e32 v2, v228, v2
	v_add_f32_e32 v2, v229, v2
	v_add_f32_e32 v2, v230, v2
	v_add_f32_e32 v2, v231, v2
	v_mov_b32_e32 v84, v2
	v_cvt_pk_bf16_f32 v80, v83, v85
	v_cvt_pk_bf16_f32 v81, v86, v87
	v_cvt_pk_bf16_f32 v82, v88, v89
	v_cvt_pk_bf16_f32 v83, v90, v91
	v_cvt_pk_bf16_f32 v76, v92, v93
	v_cvt_pk_bf16_f32 v77, v94, v95
	v_cvt_pk_bf16_f32 v78, v96, v97
	v_cvt_pk_bf16_f32 v79, v98, v99
	v_cvt_pk_bf16_f32 v68, v68, v69
	v_cvt_pk_bf16_f32 v69, v70, v71
	v_cvt_pk_bf16_f32 v70, v72, v73
	v_cvt_pk_bf16_f32 v71, v74, v75
	v_cvt_pk_bf16_f32 v72, v224, v225
	v_cvt_pk_bf16_f32 v73, v226, v227
	v_cvt_pk_bf16_f32 v74, v228, v229
	v_cvt_pk_bf16_f32 v75, v230, v231
	v_permlane32_swap_b32_e32 v2, v84
	v_permlane32_swap_b32_e32 v80, v82
	v_permlane32_swap_b32_e32 v81, v83
	v_permlane32_swap_b32_e32 v76, v78
	v_permlane32_swap_b32_e32 v77, v79
	v_permlane32_swap_b32_e32 v68, v70
	v_permlane32_swap_b32_e32 v69, v71
	v_permlane32_swap_b32_e32 v72, v74
	v_permlane32_swap_b32_e32 v73, v75
	v_cmp_gt_f32_e32 vcc, 1.0, v223
	s_cbranch_vccz .LBB0_1160
	s_and_saveexec_b64 s[10:11], s[0:1]
	ds_write_b32 v182, v223 offset:128
	s_or_b64 exec, exec, s[10:11]
	s_waitcnt lgkmcnt(0)
	ds_read_b128 v[86:89], v181 offset:224
	ds_read_b128 v[90:93], v181 offset:192
	ds_read_b128 v[94:97], v181 offset:160
	ds_read_b128 v[224:227], v181 offset:128
	s_waitcnt lgkmcnt(3)
	v_pk_mul_f32 v[66:67], v[66:67], v[88:89]
	s_waitcnt lgkmcnt(2)
	v_pk_mul_f32 v[62:63], v[62:63], v[92:93]
	s_waitcnt lgkmcnt(1)
	v_pk_mul_f32 v[58:59], v[58:59], v[96:97]
	s_waitcnt lgkmcnt(0)
	v_pk_mul_f32 v[54:55], v[54:55], v[226:227]
	v_pk_mul_f32 v[64:65], v[64:65], v[86:87]
	v_pk_mul_f32 v[60:61], v[60:61], v[90:91]
	v_pk_mul_f32 v[56:57], v[56:57], v[94:95]
	v_pk_mul_f32 v[52:53], v[52:53], v[224:225]
	v_pk_mul_f32 v[50:51], v[50:51], v[88:89]
	v_pk_mul_f32 v[46:47], v[46:47], v[92:93]
	v_pk_mul_f32 v[42:43], v[42:43], v[96:97]
	v_pk_mul_f32 v[38:39], v[38:39], v[226:227]
	v_pk_mul_f32 v[48:49], v[48:49], v[86:87]
	v_pk_mul_f32 v[44:45], v[44:45], v[90:91]
	v_pk_mul_f32 v[40:41], v[40:41], v[94:95]
	v_pk_mul_f32 v[36:37], v[36:37], v[224:225]
	v_pk_mul_f32 v[34:35], v[34:35], v[88:89]
	v_pk_mul_f32 v[30:31], v[30:31], v[92:93]
	v_pk_mul_f32 v[26:27], v[26:27], v[96:97]
	v_pk_mul_f32 v[22:23], v[22:23], v[226:227]
	v_pk_mul_f32 v[32:33], v[32:33], v[86:87]
	v_pk_mul_f32 v[28:29], v[28:29], v[90:91]
	v_pk_mul_f32 v[24:25], v[24:25], v[94:95]
	v_pk_mul_f32 v[20:21], v[20:21], v[224:225]
	v_pk_mul_f32 v[18:19], v[18:19], v[88:89]
	v_pk_mul_f32 v[14:15], v[14:15], v[92:93]
	v_pk_mul_f32 v[10:11], v[10:11], v[96:97]
	v_pk_mul_f32 v[6:7], v[6:7], v[226:227]
	v_pk_mul_f32 v[16:17], v[16:17], v[86:87]
	v_pk_mul_f32 v[12:13], v[12:13], v[90:91]
	v_pk_mul_f32 v[8:9], v[8:9], v[94:95]
	v_pk_mul_f32 v[4:5], v[4:5], v[224:225]
.LBB0_1160:
	ds_read_b64_tr_b16 v[92:93], v209 offset:0
	ds_read_b64_tr_b16 v[94:95], v209 offset:0x800
	ds_read_b64_tr_b16 v[96:97], v209 offset:0x1000
	ds_read_b64_tr_b16 v[98:99], v209 offset:0x1800
	ds_read_b64_tr_b16 v[224:225], v209 offset:0x2000
	ds_read_b64_tr_b16 v[226:227], v209 offset:0x2800
	ds_read_b64_tr_b16 v[228:229], v209 offset:0x3000
	ds_read_b64_tr_b16 v[230:231], v209 offset:0x3800
	ds_read_b64_tr_b16 v[238:239], v209 offset:0x200
	ds_read_b64_tr_b16 v[240:241], v209 offset:0xa00
	ds_read_b64_tr_b16 v[242:243], v209 offset:0x1200
	ds_read_b64_tr_b16 v[244:245], v209 offset:0x1a00
	ds_read_b64_tr_b16 v[246:247], v209 offset:0x2200
	ds_read_b64_tr_b16 v[248:249], v209 offset:0x2a00
	ds_read_b64_tr_b16 v[250:251], v209 offset:0x3200
	ds_read_b64_tr_b16 v[252:253], v209 offset:0x3a00
	s_xor_b32 s10, s13, 1
	s_lshl_b32 s11, s10, 14
	s_add_i32 s11, s11, 0
	v_add_u32_e32 v85, s11, v197
	s_lshl_b32 s10, s10, 13
	s_waitcnt vmcnt(0)
	s_waitcnt vmcnt(0)
	ds_write_b128 v85, v[164:167]
	v_add_u32_e32 v85, s11, v199
	s_add_i32 s11, s11, s10
	ds_write_b128 v85, v[160:163]
	v_add_u32_e32 v85, s11, v201
	ds_write_b128 v85, v[156:159] offset:32768
	ds_write_b128 v85, v[152:155] offset:45056
	v_add_u32_e32 v85, s11, v203
	ds_write_b128 v85, v[148:151] offset:32768
	v_lshl_add_u64 v[86:87], s[88:89], 0, v[178:179]
	v_lshl_add_u64 v[88:89], s[88:89], 0, v[176:177]
	global_load_dwordx4 v[164:167], v[86:87], off
	global_load_dwordx4 v[160:163], v[88:89], off
	v_lshl_add_u64 v[86:87], s[88:89], 0, v[170:171]
	v_lshl_add_u64 v[88:89], s[88:89], 0, v[172:173]
	global_load_dwordx4 v[156:159], v[86:87], off
	global_load_dwordx4 v[152:155], v[88:89], off
	v_lshl_add_u64 v[86:87], s[88:89], 0, v[174:175]
	global_load_dwordx4 v[148:151], v[86:87], off
	v_add_f32_e32 v2, v2, v84
	ds_read_b64_tr_b16 v[84:85], v209 offset:0x400
	ds_read_b64_tr_b16 v[86:87], v209 offset:0xc00
	ds_read_b64_tr_b16 v[88:89], v209 offset:0x1400
	ds_read_b64_tr_b16 v[90:91], v209 offset:0x1c00
	v_fmac_f32_e32 v2, v222, v223
	s_add_i32 s13, s13, 1
	s_nop 0
	s_waitcnt lgkmcnt(15)
	v_mfma_f32_32x32x16_bf16 v[52:67], v[80:83], v[92:95], v[52:67]
	s_waitcnt lgkmcnt(15)
	v_mfma_f32_32x32x16_bf16 v[52:67], v[76:79], v[96:99], v[52:67]
	s_waitcnt lgkmcnt(15)
	v_mfma_f32_32x32x16_bf16 v[52:67], v[68:71], v[224:227], v[52:67]
	s_waitcnt lgkmcnt(15)
	v_mfma_f32_32x32x16_bf16 v[52:67], v[72:75], v[228:231], v[52:67]
	s_waitcnt lgkmcnt(15)
	v_mfma_f32_32x32x16_bf16 v[36:51], v[80:83], v[238:241], v[36:51]
	s_waitcnt lgkmcnt(13)
	v_mfma_f32_32x32x16_bf16 v[36:51], v[76:79], v[242:245], v[36:51]
	s_waitcnt lgkmcnt(11)
	v_mfma_f32_32x32x16_bf16 v[36:51], v[68:71], v[246:249], v[36:51]
	s_waitcnt lgkmcnt(9)
	v_mfma_f32_32x32x16_bf16 v[36:51], v[72:75], v[250:253], v[36:51]
	s_waitcnt lgkmcnt(2)
	v_mfma_f32_32x32x16_bf16 v[20:35], v[80:83], v[84:87], v[20:35]
	ds_read_b64_tr_b16 v[84:85], v209 offset:0x2400
	ds_read_b64_tr_b16 v[86:87], v209 offset:0x2c00
	ds_read_b64_tr_b16 v[92:93], v209 offset:0x3400
	ds_read_b64_tr_b16 v[94:95], v209 offset:0x3c00
	ds_read_b64_tr_b16 v[96:97], v209 offset:0x600
	ds_read_b64_tr_b16 v[98:99], v209 offset:0xe00
	ds_read_b64_tr_b16 v[222:223], v209 offset:0x1600
	ds_read_b64_tr_b16 v[224:225], v209 offset:0x1e00
	ds_read_b64_tr_b16 v[226:227], v209 offset:0x2600
	ds_read_b64_tr_b16 v[228:229], v209 offset:0x2e00
	ds_read_b64_tr_b16 v[230:231], v209 offset:0x3600
	ds_read_b64_tr_b16 v[232:233], v209 offset:0x3e00
	s_waitcnt lgkmcnt(12)
	v_mfma_f32_32x32x16_bf16 v[20:35], v[76:79], v[88:91], v[20:35]
	s_waitcnt lgkmcnt(10)
	v_mfma_f32_32x32x16_bf16 v[20:35], v[68:71], v[84:87], v[20:35]
	s_waitcnt lgkmcnt(8)
	v_mfma_f32_32x32x16_bf16 v[20:35], v[72:75], v[92:95], v[20:35]
	s_waitcnt lgkmcnt(6)
	v_mfma_f32_32x32x16_bf16 v[4:19], v[80:83], v[96:99], v[4:19]
	s_waitcnt lgkmcnt(4)
	v_mfma_f32_32x32x16_bf16 v[4:19], v[76:79], v[222:225], v[4:19]
	s_waitcnt lgkmcnt(2)
	v_mfma_f32_32x32x16_bf16 v[4:19], v[68:71], v[226:229], v[4:19]
	s_addk_i32 s12, 0x6000
	v_lshl_add_u64 v[170:171], v[170:171], 0, s[2:3]
	v_lshl_add_u64 v[172:173], v[172:173], 0, s[2:3]
	v_lshl_add_u64 v[174:175], v[174:175], 0, s[2:3]
	v_lshl_add_u64 v[176:177], v[176:177], 0, s[4:5]
	v_lshl_add_u64 v[178:179], v[178:179], 0, s[4:5]
	v_add_u32_e32 v209, 0x4000, v209
	s_waitcnt lgkmcnt(0)
	v_mfma_f32_32x32x16_bf16 v[4:19], v[72:75], v[230:233], v[4:19]
	s_cmpk_eq_u32 s12, 0xc000
	s_barrier
	s_cbranch_scc1 .LBB0_1162
	v_mov_b32_e32 v222, v2
	s_branch .LBB0_1156
.LBB0_1162:
	v_add_u32_e32 v208, 0, v208
	v_add_u32_e32 v209, v208, v191
	ds_read_b128 v[68:71], v209 offset:32768
	ds_read_b128 v[72:75], v209 offset:45056
	v_add_u32_e32 v203, 0, v207
	v_add_u32_e32 v210, v203, v191
	ds_read_b128 v[170:173], v210 offset:32768
	ds_read_b128 v[174:177], v210 offset:45056
	s_waitcnt lgkmcnt(3)
	v_mfma_f32_32x32x16_bf16 v[84:99], v[68:71], v[144:147], 0
	v_add_u32_e32 v206, 0, v206
	v_add_u32_e32 v207, v206, v191
	ds_read_b128 v[212:215], v207 offset:32768
	ds_read_b128 v[216:219], v207 offset:45056
	v_add_u32_e32 v199, 0, v205
	v_add_u32_e32 v205, v199, v191
	ds_read_b128 v[220:223], v205 offset:32768
	ds_read_b128 v[224:227], v205 offset:45056
	v_add_u32_e32 v201, 0, v204
	v_add_u32_e32 v204, v201, v191
	ds_read_b128 v[228:231], v204 offset:32768
	ds_read_b128 v[238:241], v204 offset:45056
	v_add_u32_e32 v179, 0, v202
	s_waitcnt lgkmcnt(8)
	v_mfma_f32_32x32x16_bf16 v[68:83], v[72:75], v[144:147], 0
	v_add_u32_e32 v202, v179, v191
	ds_read_b128 v[242:245], v202 offset:32768
	ds_read_b128 v[246:249], v202 offset:45056
	v_add_u32_e32 v197, 0, v200
	v_add_u32_e32 v200, v197, v191
	ds_read_b128 v[250:253], v200 offset:32768
	s_waitcnt lgkmcnt(10)
	v_mfma_f32_32x32x16_bf16 v[84:99], v[170:173], v[140:143], v[84:99]
	s_waitcnt lgkmcnt(9)
	v_mfma_f32_32x32x16_bf16 v[68:83], v[174:177], v[140:143], v[68:83]
	s_waitcnt lgkmcnt(8)
	v_mfma_f32_32x32x16_bf16 v[84:99], v[212:215], v[136:139], v[84:99]
	ds_read_b128 v[212:215], v200 offset:45056
	s_waitcnt lgkmcnt(8)
	v_mfma_f32_32x32x16_bf16 v[68:83], v[216:219], v[136:139], v[68:83]
	s_waitcnt lgkmcnt(7)
	v_mfma_f32_32x32x16_bf16 v[84:99], v[220:223], v[132:135], v[84:99]
	s_waitcnt lgkmcnt(6)
	v_mfma_f32_32x32x16_bf16 v[68:83], v[224:227], v[132:135], v[68:83]
	s_waitcnt lgkmcnt(5)
	v_mfma_f32_32x32x16_bf16 v[84:99], v[228:231], v[128:131], v[84:99]
	s_waitcnt lgkmcnt(4)
	v_mfma_f32_32x32x16_bf16 v[68:83], v[238:241], v[128:131], v[68:83]
	s_waitcnt lgkmcnt(3)
	v_mfma_f32_32x32x16_bf16 v[84:99], v[242:245], v[124:127], v[84:99]
	s_waitcnt lgkmcnt(2)
	v_mfma_f32_32x32x16_bf16 v[68:83], v[246:249], v[124:127], v[68:83]
	v_add_u32_e32 v176, 0, v198
	v_add_u32_e32 v198, v176, v191
	ds_read_b128 v[170:173], v198 offset:32768
	ds_read_b128 v[216:219], v198 offset:45056
	v_add_u32_e32 v177, 0, v196
	v_add_u32_e32 v196, v177, v191
	ds_read_b128 v[220:223], v196 offset:32768
	ds_read_b128 v[224:227], v196 offset:45056
	v_add_u32_e32 v175, 0, v195
	v_add_u32_e32 v195, v175, v191
	ds_read_b128 v[228:231], v195 offset:32768
	ds_read_b128 v[238:241], v195 offset:45056
	v_add_u32_e32 v174, 0, v192
	s_waitcnt lgkmcnt(7)
	v_mfma_f32_32x32x16_bf16 v[84:99], v[250:253], v[120:123], v[84:99]
	v_add_u32_e32 v192, v174, v191
	s_waitcnt lgkmcnt(6)
	v_mfma_f32_32x32x16_bf16 v[68:83], v[212:215], v[120:123], v[68:83]
	s_waitcnt lgkmcnt(5)
	v_mfma_f32_32x32x16_bf16 v[84:99], v[170:173], v[116:119], v[84:99]
	s_waitcnt lgkmcnt(4)
	v_mfma_f32_32x32x16_bf16 v[68:83], v[216:219], v[116:119], v[68:83]
	s_waitcnt lgkmcnt(3)
	v_mfma_f32_32x32x16_bf16 v[84:99], v[220:223], v[112:115], v[84:99]
	s_waitcnt lgkmcnt(2)
	v_mfma_f32_32x32x16_bf16 v[68:83], v[224:227], v[112:115], v[68:83]
	s_waitcnt lgkmcnt(1)
	v_mfma_f32_32x32x16_bf16 v[84:99], v[228:231], v[108:111], v[84:99]
	v_add_u32_e32 v173, 0, v194
	v_add_u32_e32 v194, v173, v191
	ds_read_b128 v[212:215], v194 offset:32768
	ds_read_b128 v[216:219], v194 offset:45056
	ds_read_b128 v[224:227], v192 offset:32768
	ds_read_b128 v[220:223], v192 offset:45056
	v_max_f32_e32 v172, v193, v193
	s_waitcnt lgkmcnt(4)
	v_mfma_f32_32x32x16_bf16 v[68:83], v[238:241], v[108:111], v[68:83]
	s_waitcnt lgkmcnt(3)
	v_mfma_f32_32x32x16_bf16 v[84:99], v[212:215], v[104:107], v[84:99]
	s_waitcnt lgkmcnt(1)
	v_mfma_f32_32x32x16_bf16 v[84:99], v[224:227], v[100:103], v[84:99]
	v_mfma_f32_32x32x16_bf16 v[68:83], v[216:219], v[104:107], v[68:83]
	s_nop 10
	v_max_f32_e32 v170, v85, v85
	v_max_f32_e32 v171, v84, v84
	v_max_f32_e32 v170, v171, v170
	v_max3_f32 v170, v170, v86, v87
	v_max3_f32 v170, v170, v88, v89
	v_max3_f32 v170, v170, v90, v91
	v_max3_f32 v170, v170, v92, v93
	s_waitcnt lgkmcnt(0)
	v_mfma_f32_32x32x16_bf16 v[68:83], v[220:223], v[100:103], v[68:83]
	v_max3_f32 v170, v170, v94, v95
	v_max3_f32 v170, v170, v96, v97
	v_max3_f32 v170, v170, v98, v99
	s_nop 8
	v_max3_f32 v170, v170, v68, v69
	v_max3_f32 v170, v170, v70, v71
	v_max3_f32 v170, v170, v72, v73
	v_max3_f32 v170, v170, v74, v75
	v_max3_f32 v170, v170, v76, v77
	v_max3_f32 v170, v170, v78, v79
	v_max3_f32 v170, v170, v80, v81
	v_max3_f32 v170, v170, v82, v83
	v_mov_b32_e32 v171, v170
	s_nop 1
	v_permlane32_swap_b32_e32 v170, v171
	v_max_f32_e32 v171, v171, v171
	v_max_f32_e32 v170, v170, v170
	v_max_f32_e32 v170, v170, v171
	v_sub_f32_e32 v171, v170, v193
	v_cmp_ge_f32_e32 vcc, s43, v171
	s_cmp_eq_u64 vcc, exec
	v_max_f32_e32 v172, v172, v170
	s_cselect_b64 vcc, -1, 0
	v_cndmask_b32_e32 v178, v172, v193, vcc
	v_mul_f32_e32 v171, 0xbdd53b94, v178
	v_fmamk_f32 v84, v84, 0x3dd53b94, v171
	v_fmamk_f32 v85, v85, 0x3dd53b94, v171
	v_fmamk_f32 v86, v86, 0x3dd53b94, v171
	v_fmamk_f32 v87, v87, 0x3dd53b94, v171
	v_fmamk_f32 v88, v88, 0x3dd53b94, v171
	v_fmamk_f32 v89, v89, 0x3dd53b94, v171
	v_fmamk_f32 v90, v90, 0x3dd53b94, v171
	v_fmamk_f32 v91, v91, 0x3dd53b94, v171
	v_fmamk_f32 v92, v92, 0x3dd53b94, v171
	v_fmamk_f32 v93, v93, 0x3dd53b94, v171
	v_fmamk_f32 v94, v94, 0x3dd53b94, v171
	v_fmamk_f32 v95, v95, 0x3dd53b94, v171
	v_fmamk_f32 v96, v96, 0x3dd53b94, v171
	v_fmamk_f32 v97, v97, 0x3dd53b94, v171
	v_fmamk_f32 v98, v98, 0x3dd53b94, v171
	v_fmamk_f32 v99, v99, 0x3dd53b94, v171
	v_fmamk_f32 v68, v68, 0x3dd53b94, v171
	v_fmamk_f32 v69, v69, 0x3dd53b94, v171
	v_fmamk_f32 v70, v70, 0x3dd53b94, v171
	v_fmamk_f32 v71, v71, 0x3dd53b94, v171
	v_fmamk_f32 v72, v72, 0x3dd53b94, v171
	v_fmamk_f32 v73, v73, 0x3dd53b94, v171
	v_fmamk_f32 v74, v74, 0x3dd53b94, v171
	v_fmamk_f32 v75, v75, 0x3dd53b94, v171
	v_fmamk_f32 v76, v76, 0x3dd53b94, v171
	v_fmamk_f32 v77, v77, 0x3dd53b94, v171
	v_fmamk_f32 v78, v78, 0x3dd53b94, v171
	v_fmamk_f32 v79, v79, 0x3dd53b94, v171
	v_fmamk_f32 v80, v80, 0x3dd53b94, v171
	v_fmamk_f32 v81, v81, 0x3dd53b94, v171
	v_fmamk_f32 v82, v82, 0x3dd53b94, v171
	v_fmac_f32_e32 v171, 0x3dd53b94, v83
	v_exp_f32_e32 v83, v84
	v_exp_f32_e32 v84, v85
	v_exp_f32_e32 v85, v86
	v_exp_f32_e32 v86, v87
	v_exp_f32_e32 v87, v88
	v_exp_f32_e32 v88, v89
	v_exp_f32_e32 v89, v90
	v_exp_f32_e32 v90, v91
	v_exp_f32_e32 v91, v92
	v_exp_f32_e32 v92, v93
	v_exp_f32_e32 v93, v94
	v_exp_f32_e32 v94, v95
	v_exp_f32_e32 v95, v96
	v_exp_f32_e32 v96, v97
	v_exp_f32_e32 v97, v98
	v_exp_f32_e32 v98, v99
	v_exp_f32_e32 v99, v68
	v_add_f32_e32 v68, 0, v83
	v_add_f32_e32 v68, v84, v68
	v_add_f32_e32 v68, v85, v68
	v_add_f32_e32 v68, v86, v68
	v_add_f32_e32 v68, v87, v68
	v_add_f32_e32 v68, v88, v68
	v_add_f32_e32 v68, v89, v68
	v_add_f32_e32 v68, v90, v68
	v_add_f32_e32 v68, v91, v68
	v_add_f32_e32 v68, v92, v68
	v_add_f32_e32 v68, v93, v68
	v_add_f32_e32 v68, v94, v68
	v_add_f32_e32 v68, v95, v68
	v_sub_f32_e32 v170, v193, v172
	v_exp_f32_e32 v193, v69
	v_add_f32_e32 v68, v96, v68
	v_exp_f32_e32 v211, v70
	v_add_f32_e32 v68, v97, v68
	v_exp_f32_e32 v212, v71
	v_add_f32_e32 v68, v98, v68
	v_exp_f32_e32 v213, v72
	v_add_f32_e32 v68, v99, v68
	v_exp_f32_e32 v214, v73
	v_add_f32_e32 v68, v193, v68
	v_exp_f32_e32 v215, v74
	v_add_f32_e32 v68, v211, v68
	v_exp_f32_e32 v216, v75
	v_add_f32_e32 v68, v212, v68
	v_exp_f32_e32 v76, v76
	v_add_f32_e32 v68, v213, v68
	v_exp_f32_e32 v77, v77
	v_add_f32_e32 v68, v214, v68
	v_exp_f32_e32 v78, v78
	v_add_f32_e32 v68, v215, v68
	v_exp_f32_e32 v79, v79
	v_add_f32_e32 v68, v216, v68
	v_exp_f32_e32 v217, v80
	v_add_f32_e32 v68, v76, v68
	v_exp_f32_e32 v218, v81
	v_add_f32_e32 v68, v77, v68
	v_exp_f32_e32 v219, v82
	v_add_f32_e32 v68, v78, v68
	v_exp_f32_e32 v220, v171
	v_add_f32_e32 v68, v79, v68
	v_mul_f32_e32 v170, 0x3dd53b94, v170
	v_add_f32_e32 v68, v217, v68
	v_exp_f32_e32 v170, v170
	v_add_f32_e32 v68, v218, v68
	v_add_f32_e32 v68, v219, v68
	v_add_f32_e32 v171, v220, v68
	v_mov_b32_e32 v172, v171
	v_cvt_pk_bf16_f32 v72, v83, v84
	v_cvt_pk_bf16_f32 v73, v85, v86
	v_cvt_pk_bf16_f32 v74, v87, v88
	v_cvt_pk_bf16_f32 v75, v89, v90
	v_cvt_pk_bf16_f32 v68, v91, v92
	v_cvt_pk_bf16_f32 v69, v93, v94
	v_cvt_pk_bf16_f32 v70, v95, v96
	v_cvt_pk_bf16_f32 v71, v97, v98
	v_cvt_pk_bf16_f32 v80, v99, v193
	v_cvt_pk_bf16_f32 v81, v211, v212
	v_cvt_pk_bf16_f32 v82, v213, v214
	v_cvt_pk_bf16_f32 v83, v215, v216
	v_cvt_pk_bf16_f32 v76, v76, v77
	v_cvt_pk_bf16_f32 v77, v78, v79
	v_cvt_pk_bf16_f32 v78, v217, v218
	v_cvt_pk_bf16_f32 v79, v219, v220
	v_cndmask_b32_e64 v170, v170, 1.0, vcc
	v_permlane32_swap_b32_e32 v171, v172
	v_permlane32_swap_b32_e32 v72, v74
	v_permlane32_swap_b32_e32 v73, v75
	v_permlane32_swap_b32_e32 v68, v70
	v_permlane32_swap_b32_e32 v69, v71
	v_permlane32_swap_b32_e32 v80, v82
	v_permlane32_swap_b32_e32 v81, v83
	v_permlane32_swap_b32_e32 v76, v78
	v_permlane32_swap_b32_e32 v77, v79
	v_cmp_gt_f32_e32 vcc, 1.0, v170
	s_cbranch_vccz .LBB0_1166
	s_and_saveexec_b64 s[10:11], s[0:1]
	ds_write_b32 v182, v170 offset:128
	s_or_b64 exec, exec, s[10:11]
	s_waitcnt lgkmcnt(0)
	ds_read_b128 v[84:87], v181 offset:224
	ds_read_b128 v[88:91], v181 offset:192
	ds_read_b128 v[92:95], v181 offset:160
	ds_read_b128 v[96:99], v181 offset:128
	s_waitcnt lgkmcnt(3)
	v_pk_mul_f32 v[66:67], v[66:67], v[86:87]
	s_waitcnt lgkmcnt(2)
	v_pk_mul_f32 v[62:63], v[62:63], v[90:91]
	s_waitcnt lgkmcnt(1)
	v_pk_mul_f32 v[58:59], v[58:59], v[94:95]
	s_waitcnt lgkmcnt(0)
	v_pk_mul_f32 v[54:55], v[54:55], v[98:99]
	v_pk_mul_f32 v[64:65], v[64:65], v[84:85]
	v_pk_mul_f32 v[60:61], v[60:61], v[88:89]
	v_pk_mul_f32 v[56:57], v[56:57], v[92:93]
	v_pk_mul_f32 v[52:53], v[52:53], v[96:97]
	v_pk_mul_f32 v[50:51], v[50:51], v[86:87]
	v_pk_mul_f32 v[46:47], v[46:47], v[90:91]
	v_pk_mul_f32 v[42:43], v[42:43], v[94:95]
	v_pk_mul_f32 v[38:39], v[38:39], v[98:99]
	v_pk_mul_f32 v[48:49], v[48:49], v[84:85]
	v_pk_mul_f32 v[44:45], v[44:45], v[88:89]
	v_pk_mul_f32 v[40:41], v[40:41], v[92:93]
	v_pk_mul_f32 v[36:37], v[36:37], v[96:97]
	v_pk_mul_f32 v[34:35], v[34:35], v[86:87]
	v_pk_mul_f32 v[30:31], v[30:31], v[90:91]
	v_pk_mul_f32 v[26:27], v[26:27], v[94:95]
	v_pk_mul_f32 v[22:23], v[22:23], v[98:99]
	v_pk_mul_f32 v[32:33], v[32:33], v[84:85]
	v_pk_mul_f32 v[28:29], v[28:29], v[88:89]
	v_pk_mul_f32 v[24:25], v[24:25], v[92:93]
	v_pk_mul_f32 v[20:21], v[20:21], v[96:97]
	v_pk_mul_f32 v[18:19], v[18:19], v[86:87]
	v_pk_mul_f32 v[14:15], v[14:15], v[90:91]
	v_pk_mul_f32 v[10:11], v[10:11], v[94:95]
	v_pk_mul_f32 v[6:7], v[6:7], v[98:99]
	v_pk_mul_f32 v[16:17], v[16:17], v[84:85]
	v_pk_mul_f32 v[12:13], v[12:13], v[88:89]
	v_pk_mul_f32 v[8:9], v[8:9], v[92:93]
	v_pk_mul_f32 v[4:5], v[4:5], v[96:97]
.LBB0_1166:
	s_cmp_lg_u32 0, -1
	s_waitcnt vmcnt(0)
	v_or_b32_e32 v84, v190, v188
	s_cselect_b32 s10, 0, 0
	v_add3_u32 v188, v189, s10, v84
	ds_read_b64_tr_b16 v[84:85], v188 offset:0
	ds_read_b64_tr_b16 v[86:87], v188 offset:0x800
	ds_read_b64_tr_b16 v[88:89], v188 offset:0x1000
	ds_read_b64_tr_b16 v[90:91], v188 offset:0x1800
	ds_read_b64_tr_b16 v[96:97], v188 offset:0x2000
	ds_read_b64_tr_b16 v[98:99], v188 offset:0x2800
	ds_read_b64_tr_b16 v[92:93], v188 offset:0x3000
	ds_read_b64_tr_b16 v[94:95], v188 offset:0x3800
	ds_read_b64_tr_b16 v[212:213], v188 offset:0x200
	ds_read_b64_tr_b16 v[214:215], v188 offset:0xa00
	ds_read_b64_tr_b16 v[220:221], v188 offset:0x1200
	ds_read_b64_tr_b16 v[222:223], v188 offset:0x1a00
	ds_read_b64_tr_b16 v[224:225], v188 offset:0x2200
	ds_read_b64_tr_b16 v[226:227], v188 offset:0x2a00
	ds_read_b64_tr_b16 v[228:229], v188 offset:0x3200
	ds_read_b64_tr_b16 v[230:231], v188 offset:0x3a00
	ds_read_b64_tr_b16 v[238:239], v188 offset:0x400
	ds_read_b64_tr_b16 v[240:241], v188 offset:0xc00
	ds_read_b64_tr_b16 v[242:243], v188 offset:0x1400
	ds_read_b64_tr_b16 v[244:245], v188 offset:0x1c00
	ds_read_b64_tr_b16 v[246:247], v188 offset:0x2400
	ds_read_b64_tr_b16 v[248:249], v188 offset:0x2c00
	ds_read_b64_tr_b16 v[250:251], v188 offset:0x3400
	ds_read_b64_tr_b16 v[252:253], v188 offset:0x3c00
	v_add_u32_e32 v191, 0x3000, v191
	s_waitcnt vmcnt(4)
	ds_write_b128 v183, v[164:167] offset:16384
	s_waitcnt vmcnt(3)
	ds_write_b128 v184, v[160:163] offset:16384
	s_waitcnt vmcnt(2)
	ds_write_b128 v185, v[156:159] offset:57344
	s_waitcnt vmcnt(1)
	ds_write_b128 v186, v[152:155] offset:57344
	s_waitcnt vmcnt(0)
	ds_write_b128 v187, v[148:151] offset:57344
	s_nop 0
	s_waitcnt lgkmcnt(15)
	v_mfma_f32_32x32x16_bf16 v[52:67], v[72:75], v[84:87], v[52:67]
	ds_read_b64_tr_b16 v[84:85], v188 offset:0x600
	ds_read_b64_tr_b16 v[86:87], v188 offset:0xe00
	ds_read_b64_tr_b16 v[148:149], v188 offset:0x1600
	ds_read_b64_tr_b16 v[150:151], v188 offset:0x1e00
	ds_read_b64_tr_b16 v[152:153], v188 offset:0x2600
	ds_read_b64_tr_b16 v[154:155], v188 offset:0x2e00
	ds_read_b64_tr_b16 v[156:157], v188 offset:0x3600
	ds_read_b64_tr_b16 v[158:159], v188 offset:0x3e00
	s_waitcnt lgkmcnt(15)
	v_mfma_f32_32x32x16_bf16 v[52:67], v[68:71], v[88:91], v[52:67]
	s_waitcnt lgkmcnt(15)
	v_mfma_f32_32x32x16_bf16 v[52:67], v[80:83], v[96:99], v[52:67]
	s_waitcnt lgkmcnt(15)
	v_mfma_f32_32x32x16_bf16 v[52:67], v[76:79], v[92:95], v[52:67]
	s_waitcnt lgkmcnt(15)
	v_mfma_f32_32x32x16_bf16 v[36:51], v[72:75], v[212:215], v[36:51]
	s_waitcnt lgkmcnt(15)
	v_mfma_f32_32x32x16_bf16 v[36:51], v[68:71], v[220:223], v[36:51]
	s_waitcnt lgkmcnt(15)
	v_mfma_f32_32x32x16_bf16 v[36:51], v[80:83], v[224:227], v[36:51]
	s_waitcnt lgkmcnt(15)
	v_mfma_f32_32x32x16_bf16 v[36:51], v[76:79], v[228:231], v[36:51]
	s_waitcnt lgkmcnt(15)
	v_mfma_f32_32x32x16_bf16 v[20:35], v[72:75], v[238:241], v[20:35]
	s_waitcnt lgkmcnt(15)
	v_mfma_f32_32x32x16_bf16 v[20:35], v[68:71], v[242:245], v[20:35]
	s_waitcnt lgkmcnt(15)
	v_mfma_f32_32x32x16_bf16 v[20:35], v[80:83], v[246:249], v[20:35]
	s_waitcnt lgkmcnt(13)
	v_mfma_f32_32x32x16_bf16 v[20:35], v[76:79], v[250:253], v[20:35]
	s_waitcnt lgkmcnt(6)
	v_mfma_f32_32x32x16_bf16 v[4:19], v[72:75], v[84:87], v[4:19]
	s_waitcnt lgkmcnt(4)
	v_mfma_f32_32x32x16_bf16 v[4:19], v[68:71], v[148:151], v[4:19]
	s_waitcnt lgkmcnt(2)
	v_mfma_f32_32x32x16_bf16 v[4:19], v[80:83], v[152:155], v[4:19]
	s_barrier
	ds_read_b128 v[68:71], v209 offset:57344
	ds_read_b128 v[148:151], v210 offset:57344
	s_waitcnt lgkmcnt(2)
	v_mfma_f32_32x32x16_bf16 v[4:19], v[76:79], v[156:159], v[4:19]
	v_add_u32_e32 v72, v208, v191
	s_waitcnt lgkmcnt(1)
	v_mfma_f32_32x32x16_bf16 v[84:99], v[68:71], v[144:147], 0
	ds_read_b128 v[68:71], v72 offset:57344
	v_add_u32_e32 v72, v203, v191
	ds_read_b128 v[152:155], v72 offset:57344
	ds_read_b128 v[156:159], v205 offset:57344
	ds_read_b128 v[164:167], v207 offset:57344
	s_waitcnt lgkmcnt(4)
	v_mfma_f32_32x32x16_bf16 v[84:99], v[148:151], v[140:143], v[84:99]
	v_add_u32_e32 v148, v206, v191
	ds_read_b128 v[206:209], v148 offset:57344
	s_waitcnt lgkmcnt(4)
	v_mfma_f32_32x32x16_bf16 v[68:83], v[68:71], v[144:147], 0
	s_waitcnt lgkmcnt(3)
	v_mfma_f32_32x32x16_bf16 v[68:83], v[152:155], v[140:143], v[68:83]
	s_waitcnt lgkmcnt(1)
	v_mfma_f32_32x32x16_bf16 v[84:99], v[164:167], v[136:139], v[84:99]
	v_add_u32_e32 v148, v199, v191
	ds_read_b128 v[148:151], v148 offset:57344
	ds_read_b128 v[144:147], v202 offset:57344
	ds_read_b128 v[164:167], v204 offset:57344
	s_waitcnt lgkmcnt(3)
	v_mfma_f32_32x32x16_bf16 v[68:83], v[206:209], v[136:139], v[68:83]
	v_add_u32_e32 v140, v201, v191
	ds_read_b128 v[136:139], v140 offset:57344
	v_mfma_f32_32x32x16_bf16 v[84:99], v[156:159], v[132:135], v[84:99]
	s_waitcnt lgkmcnt(3)
	v_mfma_f32_32x32x16_bf16 v[68:83], v[148:151], v[132:135], v[68:83]
	s_waitcnt lgkmcnt(1)
	v_mfma_f32_32x32x16_bf16 v[84:99], v[164:167], v[128:131], v[84:99]
	v_add_u32_e32 v140, v179, v191
	ds_read_b128 v[140:143], v140 offset:57344
	ds_read_b128 v[154:157], v198 offset:57344
	ds_read_b128 v[158:161], v200 offset:57344
	s_waitcnt lgkmcnt(3)
	v_mfma_f32_32x32x16_bf16 v[68:83], v[136:139], v[128:131], v[68:83]
	v_add_u32_e32 v132, v197, v191
	ds_read_b128 v[128:131], v132 offset:57344
	v_mfma_f32_32x32x16_bf16 v[84:99], v[144:147], v[124:127], v[84:99]
	s_waitcnt lgkmcnt(3)
	v_mfma_f32_32x32x16_bf16 v[68:83], v[140:143], v[124:127], v[68:83]
	s_waitcnt lgkmcnt(1)
	v_mfma_f32_32x32x16_bf16 v[84:99], v[158:161], v[120:123], v[84:99]
	v_add_u32_e32 v132, v176, v191
	ds_read_b128 v[132:135], v132 offset:57344
	ds_read_b128 v[136:139], v195 offset:57344
	ds_read_b128 v[140:143], v196 offset:57344
	s_waitcnt lgkmcnt(3)
	v_mfma_f32_32x32x16_bf16 v[68:83], v[128:131], v[120:123], v[68:83]
	v_add_u32_e32 v124, v177, v191
	ds_read_b128 v[120:123], v124 offset:57344
	v_mfma_f32_32x32x16_bf16 v[84:99], v[154:157], v[116:119], v[84:99]
	s_waitcnt lgkmcnt(3)
	v_mfma_f32_32x32x16_bf16 v[68:83], v[132:135], v[116:119], v[68:83]
	s_waitcnt lgkmcnt(1)
	v_mfma_f32_32x32x16_bf16 v[84:99], v[140:143], v[112:115], v[84:99]
	v_add_u32_e32 v124, v175, v191
	ds_read_b128 v[124:127], v124 offset:57344
	ds_read_b128 v[116:119], v194 offset:57344
	ds_read_b128 v[128:131], v192 offset:57344
	s_waitcnt lgkmcnt(3)
	v_mfma_f32_32x32x16_bf16 v[68:83], v[120:123], v[112:115], v[68:83]
	v_mfma_f32_32x32x16_bf16 v[84:99], v[136:139], v[108:111], v[84:99]
	s_waitcnt lgkmcnt(2)
	v_mfma_f32_32x32x16_bf16 v[68:83], v[124:127], v[108:111], v[68:83]
	s_waitcnt lgkmcnt(1)
	v_mfma_f32_32x32x16_bf16 v[84:99], v[116:119], v[104:107], v[84:99]
	v_add_u32_e32 v108, v173, v191
	ds_read_b128 v[108:111], v108 offset:57344
	s_waitcnt lgkmcnt(1)
	v_mfma_f32_32x32x16_bf16 v[84:99], v[128:131], v[100:103], v[84:99]
	v_add_u32_e32 v112, v174, v191
	ds_read_b128 v[112:115], v112 offset:57344
	s_waitcnt lgkmcnt(1)
	v_mfma_f32_32x32x16_bf16 v[68:83], v[108:111], v[104:107], v[68:83]
	s_nop 7
	v_max_f32_e32 v116, v85, v85
	v_max_f32_e32 v117, v84, v84
	v_max_f32_e32 v116, v117, v116
	v_max3_f32 v104, v116, v86, v87
	v_max3_f32 v104, v104, v88, v89
	v_max3_f32 v104, v104, v90, v91
	v_max3_f32 v104, v104, v92, v93
	s_waitcnt lgkmcnt(0)
	v_mfma_f32_32x32x16_bf16 v[68:83], v[112:115], v[100:103], v[68:83]
	v_max3_f32 v104, v104, v94, v95
	v_max3_f32 v104, v104, v96, v97
	v_max3_f32 v104, v104, v98, v99
	v_max_f32_e32 v102, v178, v178
	s_nop 7
	v_max3_f32 v100, v104, v68, v69
	v_max3_f32 v100, v100, v70, v71
	v_max3_f32 v100, v100, v72, v73
	v_max3_f32 v100, v100, v74, v75
	v_max3_f32 v100, v100, v76, v77
	v_max3_f32 v100, v100, v78, v79
	v_max3_f32 v100, v100, v80, v81
	v_max3_f32 v100, v100, v82, v83
	v_mov_b32_e32 v101, v100
	s_nop 1
	v_permlane32_swap_b32_e32 v100, v101
	v_max_f32_e32 v101, v101, v101
	v_max_f32_e32 v100, v100, v100
	v_max_f32_e32 v100, v100, v101
	v_sub_f32_e32 v101, v100, v178
	v_cmp_ge_f32_e32 vcc, s43, v101
	s_cmp_eq_u64 vcc, exec
	v_max_f32_e32 v102, v102, v100
	s_cselect_b64 vcc, -1, 0
	v_cndmask_b32_e32 v101, v102, v178, vcc
	v_mul_f32_e32 v101, 0xbdd53b94, v101
	v_fmamk_f32 v84, v84, 0x3dd53b94, v101
	v_fmamk_f32 v85, v85, 0x3dd53b94, v101
	v_fmamk_f32 v86, v86, 0x3dd53b94, v101
	v_fmamk_f32 v87, v87, 0x3dd53b94, v101
	v_fmamk_f32 v88, v88, 0x3dd53b94, v101
	v_fmamk_f32 v89, v89, 0x3dd53b94, v101
	v_fmamk_f32 v90, v90, 0x3dd53b94, v101
	v_fmamk_f32 v91, v91, 0x3dd53b94, v101
	v_fmamk_f32 v92, v92, 0x3dd53b94, v101
	v_fmamk_f32 v93, v93, 0x3dd53b94, v101
	v_fmamk_f32 v94, v94, 0x3dd53b94, v101
	v_fmamk_f32 v95, v95, 0x3dd53b94, v101
	v_fmamk_f32 v96, v96, 0x3dd53b94, v101
	v_fmamk_f32 v97, v97, 0x3dd53b94, v101
	v_fmamk_f32 v98, v98, 0x3dd53b94, v101
	v_fmamk_f32 v99, v99, 0x3dd53b94, v101
	v_fmamk_f32 v68, v68, 0x3dd53b94, v101
	v_fmamk_f32 v69, v69, 0x3dd53b94, v101
	v_fmamk_f32 v70, v70, 0x3dd53b94, v101
	v_fmamk_f32 v71, v71, 0x3dd53b94, v101
	v_fmamk_f32 v72, v72, 0x3dd53b94, v101
	v_fmamk_f32 v73, v73, 0x3dd53b94, v101
	v_fmamk_f32 v74, v74, 0x3dd53b94, v101
	v_fmamk_f32 v75, v75, 0x3dd53b94, v101
	v_fmamk_f32 v76, v76, 0x3dd53b94, v101
	v_fmamk_f32 v77, v77, 0x3dd53b94, v101
	v_fmamk_f32 v78, v78, 0x3dd53b94, v101
	v_fmamk_f32 v79, v79, 0x3dd53b94, v101
	v_fmamk_f32 v80, v80, 0x3dd53b94, v101
	v_fmamk_f32 v81, v81, 0x3dd53b94, v101
	v_fmamk_f32 v82, v82, 0x3dd53b94, v101
	v_fmac_f32_e32 v101, 0x3dd53b94, v83
	v_exp_f32_e32 v83, v84
	v_sub_f32_e32 v100, v178, v102
	v_exp_f32_e32 v102, v85
	v_exp_f32_e32 v86, v86
	v_exp_f32_e32 v87, v87
	v_exp_f32_e32 v88, v88
	v_exp_f32_e32 v103, v68
	v_add_f32_e32 v68, 0, v83
	v_exp_f32_e32 v89, v89
	v_add_f32_e32 v68, v102, v68
	v_exp_f32_e32 v90, v90
	v_add_f32_e32 v68, v86, v68
	v_exp_f32_e32 v91, v91
	v_add_f32_e32 v68, v87, v68
	v_exp_f32_e32 v92, v92
	v_add_f32_e32 v68, v88, v68
	v_exp_f32_e32 v93, v93
	v_add_f32_e32 v68, v89, v68
	v_exp_f32_e32 v94, v94
	v_add_f32_e32 v68, v90, v68
	v_exp_f32_e32 v95, v95
	v_add_f32_e32 v68, v91, v68
	v_exp_f32_e32 v96, v96
	v_add_f32_e32 v68, v92, v68
	v_exp_f32_e32 v97, v97
	v_add_f32_e32 v68, v93, v68
	v_exp_f32_e32 v98, v98
	v_add_f32_e32 v68, v94, v68
	v_exp_f32_e32 v99, v99
	v_add_f32_e32 v68, v95, v68
	v_add_f32_e32 v68, v96, v68
	v_exp_f32_e32 v104, v69
	v_add_f32_e32 v68, v97, v68
	v_exp_f32_e32 v105, v70
	v_add_f32_e32 v68, v98, v68
	v_exp_f32_e32 v106, v71
	v_add_f32_e32 v68, v99, v68
	v_exp_f32_e32 v107, v72
	v_add_f32_e32 v68, v103, v68
	v_exp_f32_e32 v108, v73
	v_add_f32_e32 v68, v104, v68
	v_exp_f32_e32 v109, v74
	v_add_f32_e32 v68, v105, v68
	v_exp_f32_e32 v110, v75
	v_add_f32_e32 v68, v106, v68
	v_exp_f32_e32 v76, v76
	v_add_f32_e32 v68, v107, v68
	v_exp_f32_e32 v77, v77
	v_add_f32_e32 v68, v108, v68
	v_exp_f32_e32 v78, v78
	v_add_f32_e32 v68, v109, v68
	v_exp_f32_e32 v79, v79
	v_add_f32_e32 v68, v110, v68
	v_exp_f32_e32 v111, v80
	v_add_f32_e32 v68, v76, v68
	v_exp_f32_e32 v112, v81
	v_add_f32_e32 v68, v77, v68
	v_exp_f32_e32 v113, v82
	v_add_f32_e32 v68, v78, v68
	v_exp_f32_e32 v101, v101
	v_add_f32_e32 v68, v79, v68
	v_mul_f32_e32 v100, 0x3dd53b94, v100
	v_add_f32_e32 v68, v111, v68
	v_exp_f32_e32 v100, v100
	v_add_f32_e32 v68, v112, v68
	v_add_f32_e32 v68, v113, v68
	v_add_f32_e32 v84, v101, v68
	v_mov_b32_e32 v85, v84
	v_cvt_pk_bf16_f32 v72, v83, v102
	v_cvt_pk_bf16_f32 v73, v86, v87
	v_cvt_pk_bf16_f32 v74, v88, v89
	v_cvt_pk_bf16_f32 v75, v90, v91
	v_cvt_pk_bf16_f32 v68, v92, v93
	v_cvt_pk_bf16_f32 v69, v94, v95
	v_cvt_pk_bf16_f32 v70, v96, v97
	v_cvt_pk_bf16_f32 v71, v98, v99
	v_cvt_pk_bf16_f32 v80, v103, v104
	v_cvt_pk_bf16_f32 v81, v105, v106
	v_cvt_pk_bf16_f32 v82, v107, v108
	v_cvt_pk_bf16_f32 v83, v109, v110
	v_cvt_pk_bf16_f32 v76, v76, v77
	v_cvt_pk_bf16_f32 v77, v78, v79
	v_cvt_pk_bf16_f32 v78, v111, v112
	v_cvt_pk_bf16_f32 v79, v113, v101
	v_cndmask_b32_e64 v100, v100, 1.0, vcc
	v_permlane32_swap_b32_e32 v84, v85
	v_permlane32_swap_b32_e32 v72, v74
	v_permlane32_swap_b32_e32 v73, v75
	v_permlane32_swap_b32_e32 v68, v70
	v_permlane32_swap_b32_e32 v69, v71
	v_permlane32_swap_b32_e32 v80, v82
	v_permlane32_swap_b32_e32 v81, v83
	v_permlane32_swap_b32_e32 v76, v78
	v_permlane32_swap_b32_e32 v77, v79
	v_cmp_gt_f32_e32 vcc, 1.0, v100
	s_cbranch_vccz .LBB0_1170
	s_and_saveexec_b64 s[10:11], s[0:1]
	ds_write_b32 v182, v100 offset:128
	s_or_b64 exec, exec, s[10:11]
	s_waitcnt lgkmcnt(0)
	ds_read_b128 v[86:89], v181 offset:224
	ds_read_b128 v[90:93], v181 offset:192
	ds_read_b128 v[94:97], v181 offset:160
	ds_read_b128 v[102:105], v181 offset:128
	s_waitcnt lgkmcnt(3)
	v_pk_mul_f32 v[66:67], v[66:67], v[88:89]
	s_waitcnt lgkmcnt(2)
	v_pk_mul_f32 v[62:63], v[62:63], v[92:93]
	s_waitcnt lgkmcnt(1)
	v_pk_mul_f32 v[58:59], v[58:59], v[96:97]
	s_waitcnt lgkmcnt(0)
	v_pk_mul_f32 v[54:55], v[54:55], v[104:105]
	v_pk_mul_f32 v[64:65], v[64:65], v[86:87]
	v_pk_mul_f32 v[60:61], v[60:61], v[90:91]
	v_pk_mul_f32 v[56:57], v[56:57], v[94:95]
	v_pk_mul_f32 v[52:53], v[52:53], v[102:103]
	v_pk_mul_f32 v[50:51], v[50:51], v[88:89]
	v_pk_mul_f32 v[46:47], v[46:47], v[92:93]
	v_pk_mul_f32 v[42:43], v[42:43], v[96:97]
	v_pk_mul_f32 v[38:39], v[38:39], v[104:105]
	v_pk_mul_f32 v[48:49], v[48:49], v[86:87]
	v_pk_mul_f32 v[44:45], v[44:45], v[90:91]
	v_pk_mul_f32 v[40:41], v[40:41], v[94:95]
	v_pk_mul_f32 v[36:37], v[36:37], v[102:103]
	v_pk_mul_f32 v[34:35], v[34:35], v[88:89]
	v_pk_mul_f32 v[30:31], v[30:31], v[92:93]
	v_pk_mul_f32 v[26:27], v[26:27], v[96:97]
	v_pk_mul_f32 v[22:23], v[22:23], v[104:105]
	v_pk_mul_f32 v[32:33], v[32:33], v[86:87]
	v_pk_mul_f32 v[28:29], v[28:29], v[90:91]
	v_pk_mul_f32 v[24:25], v[24:25], v[94:95]
	v_pk_mul_f32 v[20:21], v[20:21], v[102:103]
	v_pk_mul_f32 v[18:19], v[18:19], v[88:89]
	v_pk_mul_f32 v[14:15], v[14:15], v[92:93]
	v_pk_mul_f32 v[10:11], v[10:11], v[96:97]
	v_pk_mul_f32 v[6:7], v[6:7], v[104:105]
	v_pk_mul_f32 v[16:17], v[16:17], v[86:87]
	v_pk_mul_f32 v[12:13], v[12:13], v[90:91]
	v_pk_mul_f32 v[8:9], v[8:9], v[94:95]
	v_pk_mul_f32 v[4:5], v[4:5], v[102:103]
.LBB0_1170:
	v_add_u32_e32 v98, 0x4000, v188
	ds_read_b64_tr_b16 v[86:87], v98 offset:0
	ds_read_b64_tr_b16 v[88:89], v98 offset:0x800
	ds_read_b64_tr_b16 v[90:91], v98 offset:0x1000
	ds_read_b64_tr_b16 v[92:93], v98 offset:0x1800
	ds_read_b64_tr_b16 v[102:103], v98 offset:0x2000
	ds_read_b64_tr_b16 v[104:105], v98 offset:0x2800
	ds_read_b64_tr_b16 v[94:95], v98 offset:0x3000
	ds_read_b64_tr_b16 v[96:97], v98 offset:0x3800
	ds_read_b64_tr_b16 v[110:111], v98 offset:0x200
	ds_read_b64_tr_b16 v[112:113], v98 offset:0xa00
	ds_read_b64_tr_b16 v[118:119], v98 offset:0x1200
	ds_read_b64_tr_b16 v[120:121], v98 offset:0x1a00
	ds_read_b64_tr_b16 v[122:123], v98 offset:0x2200
	ds_read_b64_tr_b16 v[124:125], v98 offset:0x2a00
	ds_read_b64_tr_b16 v[126:127], v98 offset:0x3200
	ds_read_b64_tr_b16 v[128:129], v98 offset:0x3a00
	ds_read_b64_tr_b16 v[130:131], v98 offset:0x400
	ds_read_b64_tr_b16 v[132:133], v98 offset:0xc00
	ds_read_b64_tr_b16 v[134:135], v98 offset:0x1400
	ds_read_b64_tr_b16 v[136:137], v98 offset:0x1c00
	ds_read_b64_tr_b16 v[138:139], v98 offset:0x2400
	ds_read_b64_tr_b16 v[140:141], v98 offset:0x2c00
	ds_read_b64_tr_b16 v[142:143], v98 offset:0x3400
	ds_read_b64_tr_b16 v[144:145], v98 offset:0x3c00
	ds_read_b64_tr_b16 v[146:147], v98 offset:0x600
	ds_read_b64_tr_b16 v[148:149], v98 offset:0xe00
	s_nop 0
	s_waitcnt lgkmcnt(15)
	v_mfma_f32_32x32x16_bf16 v[52:67], v[72:75], v[86:89], v[52:67]
	s_waitcnt lgkmcnt(15)
	v_mfma_f32_32x32x16_bf16 v[52:67], v[68:71], v[90:93], v[52:67]
	ds_read_b64_tr_b16 v[90:91], v98 offset:0x1600
	ds_read_b64_tr_b16 v[92:93], v98 offset:0x1e00
	ds_read_b64_tr_b16 v[154:155], v98 offset:0x2600
	ds_read_b64_tr_b16 v[156:157], v98 offset:0x2e00
	ds_read_b64_tr_b16 v[86:87], v98 offset:0x3600
	ds_read_b64_tr_b16 v[88:89], v98 offset:0x3e00
	s_waitcnt lgkmcnt(15)
	v_mfma_f32_32x32x16_bf16 v[52:67], v[80:83], v[102:105], v[52:67]
	s_waitcnt lgkmcnt(15)
	v_mfma_f32_32x32x16_bf16 v[52:67], v[76:79], v[94:97], v[52:67]
	s_waitcnt lgkmcnt(15)
	v_mfma_f32_32x32x16_bf16 v[36:51], v[72:75], v[110:113], v[36:51]
	s_waitcnt lgkmcnt(15)
	v_mfma_f32_32x32x16_bf16 v[36:51], v[68:71], v[118:121], v[36:51]
	s_waitcnt lgkmcnt(15)
	v_mfma_f32_32x32x16_bf16 v[36:51], v[80:83], v[122:125], v[36:51]
	s_waitcnt lgkmcnt(15)
	v_mfma_f32_32x32x16_bf16 v[36:51], v[76:79], v[126:129], v[36:51]
	s_waitcnt lgkmcnt(14)
	v_mfma_f32_32x32x16_bf16 v[20:35], v[72:75], v[130:133], v[20:35]
	s_waitcnt lgkmcnt(12)
	v_mfma_f32_32x32x16_bf16 v[20:35], v[68:71], v[134:137], v[20:35]
	s_waitcnt lgkmcnt(10)
	v_mfma_f32_32x32x16_bf16 v[20:35], v[80:83], v[138:141], v[20:35]
	s_waitcnt lgkmcnt(8)
	v_mfma_f32_32x32x16_bf16 v[20:35], v[76:79], v[142:145], v[20:35]
	s_waitcnt lgkmcnt(6)
	v_mfma_f32_32x32x16_bf16 v[4:19], v[72:75], v[146:149], v[4:19]
	s_waitcnt lgkmcnt(4)
	v_mfma_f32_32x32x16_bf16 v[4:19], v[68:71], v[90:93], v[4:19]
	s_waitcnt lgkmcnt(2)
	v_mfma_f32_32x32x16_bf16 v[4:19], v[80:83], v[154:157], v[4:19]
	s_barrier
	s_waitcnt lgkmcnt(0)
	v_mfma_f32_32x32x16_bf16 v[4:19], v[76:79], v[86:89], v[4:19]
	s_and_saveexec_b64 s[10:11], s[0:1]
	s_cbranch_execz .LBB0_1154
	v_add_f32_e32 v68, v171, v172
	v_fmac_f32_e32 v68, v2, v170
	v_add_f32_e32 v2, v84, v85
	v_fmac_f32_e32 v2, v68, v100
	ds_write_b32 v182, v2
	s_branch .LBB0_1154
